# v26
# baseline (speedup 1.0000x reference)
; __device__ __forceinline__ unsigned pk2(float lo, float hi) { return pg8::cvt_pk_bf16(lo, hi); }
; __device__ __forceinline__ void convert_p(const Ctx& C) {
;     const float* p = C.in[1]; bf16* o = (bf16*)(C.ws + WS_PBF); const size_t n8 = (size_t)2 * M * PLE / 8;
;     for (size_t i = (size_t)C.bid * NTHR + C.tid; i < n8; i += (size_t)C.G * NTHR) {
;         const f32x4 a = __builtin_nontemporal_load((const f32x4*)(p + i * 8)), b = __builtin_nontemporal_load((const f32x4*)(p + i * 8 + 4));
;         v4u w; w.x = pk2(a[0], a[1]); w.y = pk2(a[2], a[3]); w.z = pk2(b[0], b[1]); w.w = pk2(b[2], b[3]);
;         *(v4u*)(o + i * 8) = w; }
; }
; __device__ __forceinline__ void xcvt_pass(const Ctx& C, const float* X, bf16* XB) {
;     const int gw = C.bid * 8 + C.wave, NGW = C.G * 8; float* SS = (float*)(C.ws + WS_SS);
;     for (int m = gw; m < M; m += NGW) {
;         const f32x4* xr = (const f32x4*)(X + (size_t)m * D) + C.lane; v2u* o = (v2u*)(XB + (size_t)m * D) + C.lane; float s = 0.f;
; #pragma unroll
;         for (int j = 0; j < 8; ++j) { const f32x4 v = __builtin_nontemporal_load(xr + 64 * j); const v2u w = (v2u){pk2(v[0], v[1]), pk2(v[2], v[3])}; o[64 * j] = w;
;             const float x0 = __uint_as_float(w.x << 16), x1 = __uint_as_float(w.x & 0xffff0000u), x2 = __uint_as_float(w.y << 16), x3 = __uint_as_float(w.y & 0xffff0000u);
;             s += (x0 * x0 + x1 * x1) + (x2 * x2 + x3 * x3); }
.Lp0_zp_done:
	s_mov_b64 exec, s[8:9]
	v_lshlrev_b32_e32 v12, 5, v11
	v_lshlrev_b32_e32 v13, 4, v11
	s_mov_b32 s10, s66
	s_mov_b32 s11, s67
	global_load_dwordx4 v[20:23], v12, s[10:11] nt
	global_load_dwordx4 v[24:27], v12, s[10:11] offset:16 nt
	s_add_u32 s10, s10, 0x400000
	s_addc_u32 s11, s11, 0
	global_load_dwordx4 v[28:31], v12, s[10:11] nt
	global_load_dwordx4 v[32:35], v12, s[10:11] offset:16 nt
	s_add_u32 s10, s10, 0x400000
	s_addc_u32 s11, s11, 0
	global_load_dwordx4 v[36:39], v12, s[10:11] nt
	global_load_dwordx4 v[40:43], v12, s[10:11] offset:16 nt
	s_add_u32 s10, s10, 0x400000
	s_addc_u32 s11, s11, 0
	global_load_dwordx4 v[44:47], v12, s[10:11] nt
	global_load_dwordx4 v[48:51], v12, s[10:11] offset:16 nt
	s_add_u32 s10, s10, 0x400000
	s_addc_u32 s11, s11, 0
	global_load_dwordx4 v[52:55], v12, s[10:11] nt
	global_load_dwordx4 v[56:59], v12, s[10:11] offset:16 nt
	s_add_u32 s10, s10, 0x400000
	s_addc_u32 s11, s11, 0
	global_load_dwordx4 v[60:63], v12, s[10:11] nt
	global_load_dwordx4 v[64:67], v12, s[10:11] offset:16 nt
	s_add_u32 s10, s10, 0x400000
	s_addc_u32 s11, s11, 0
	global_load_dwordx4 v[68:71], v12, s[10:11] nt
	global_load_dwordx4 v[72:75], v12, s[10:11] offset:16 nt
	s_add_u32 s10, s10, 0x400000
	s_addc_u32 s11, s11, 0
	global_load_dwordx4 v[76:79], v12, s[10:11] nt
	global_load_dwordx4 v[80:83], v12, s[10:11] offset:16 nt
	s_add_u32 s12, s48, 0xd400000
	s_addc_u32 s13, s49, 0
	s_waitcnt vmcnt(14)
	v_cvt_pk_bf16_f32 v84, v20, v21
	v_cvt_pk_bf16_f32 v85, v22, v23
	v_cvt_pk_bf16_f32 v86, v24, v25
	v_cvt_pk_bf16_f32 v87, v26, v27
	global_store_dwordx4 v13, v[84:87], s[12:13] sc0 sc1
	s_add_u32 s12, s12, 0x200000
	s_addc_u32 s13, s13, 0
	s_waitcnt vmcnt(13)
	v_cvt_pk_bf16_f32 v88, v28, v29
	v_cvt_pk_bf16_f32 v89, v30, v31
	v_cvt_pk_bf16_f32 v90, v32, v33
	v_cvt_pk_bf16_f32 v91, v34, v35
	global_store_dwordx4 v13, v[88:91], s[12:13] sc0 sc1
	s_add_u32 s12, s12, 0x200000
	s_addc_u32 s13, s13, 0
	s_waitcnt vmcnt(12)
	v_cvt_pk_bf16_f32 v92, v36, v37
	v_cvt_pk_bf16_f32 v93, v38, v39
	v_cvt_pk_bf16_f32 v94, v40, v41
	v_cvt_pk_bf16_f32 v95, v42, v43
	global_store_dwordx4 v13, v[92:95], s[12:13] sc0 sc1
	s_add_u32 s12, s12, 0x200000
	s_addc_u32 s13, s13, 0
	s_waitcnt vmcnt(11)
	v_cvt_pk_bf16_f32 v96, v44, v45
	v_cvt_pk_bf16_f32 v97, v46, v47
	v_cvt_pk_bf16_f32 v98, v48, v49
	v_cvt_pk_bf16_f32 v99, v50, v51
	global_store_dwordx4 v13, v[96:99], s[12:13] sc0 sc1
	s_add_u32 s12, s12, 0x200000
	s_addc_u32 s13, s13, 0
	s_waitcnt vmcnt(10)
	v_cvt_pk_bf16_f32 v100, v52, v53
	v_cvt_pk_bf16_f32 v101, v54, v55
	v_cvt_pk_bf16_f32 v102, v56, v57
	v_cvt_pk_bf16_f32 v103, v58, v59
	global_store_dwordx4 v13, v[100:103], s[12:13] sc0 sc1
	s_add_u32 s12, s12, 0x200000
	s_addc_u32 s13, s13, 0
	s_waitcnt vmcnt(9)
	v_cvt_pk_bf16_f32 v104, v60, v61
	v_cvt_pk_bf16_f32 v105, v62, v63
	v_cvt_pk_bf16_f32 v106, v64, v65
	v_cvt_pk_bf16_f32 v107, v66, v67
	global_store_dwordx4 v13, v[104:107], s[12:13] sc0 sc1
	s_add_u32 s12, s12, 0x200000
	s_addc_u32 s13, s13, 0
	s_waitcnt vmcnt(8)
	v_cvt_pk_bf16_f32 v108, v68, v69
	v_cvt_pk_bf16_f32 v109, v70, v71
	v_cvt_pk_bf16_f32 v110, v72, v73
	v_cvt_pk_bf16_f32 v111, v74, v75
	global_store_dwordx4 v13, v[108:111], s[12:13] sc0 sc1
	s_add_u32 s12, s12, 0x200000
	s_addc_u32 s13, s13, 0
	s_waitcnt vmcnt(7)
	v_cvt_pk_bf16_f32 v112, v76, v77
	v_cvt_pk_bf16_f32 v113, v78, v79
	v_cvt_pk_bf16_f32 v114, v80, v81
	v_cvt_pk_bf16_f32 v115, v82, v83
	global_store_dwordx4 v13, v[112:115], s[12:13] sc0 sc1
	s_mov_b32 s58, s2
	s_lshl_b32 s58, s58, 3
	v_readfirstlane_b32 s6, v234
	s_lshr_b32 s6, s6, 6
	s_add_u32 s58, s58, s6
	v_lshlrev_b32_e32 v14, 4, v1
	v_lshlrev_b32_e32 v15, 3, v1
	v_lshlrev_b32_e32 v16, 2, v1
	v_xor_b32_e32 v120, 4, v16
	v_xor_b32_e32 v121, 8, v16
	v_xor_b32_e32 v122, 16, v16
	v_xor_b32_e32 v123, 32, v16
	v_xor_b32_e32 v124, 64, v16
	v_xor_b32_e32 v125, 128, v16
	s_lshl_b32 s6, s58, 13
	s_lshr_b32 s7, s58, 19
	s_add_u32 s10, s64, s6
	s_addc_u32 s11, s65, s7
	s_add_u32 s10, s10, 0x1000
	s_addc_u32 s11, s11, 0
	global_load_dwordx4 v[20:23], v14, s[10:11] offset:-4096 nt
	global_load_dwordx4 v[24:27], v14, s[10:11] offset:-3072 nt
	global_load_dwordx4 v[28:31], v14, s[10:11] offset:-2048 nt
	global_load_dwordx4 v[32:35], v14, s[10:11] offset:-1024 nt
	global_load_dwordx4 v[36:39], v14, s[10:11] offset:0 nt
	global_load_dwordx4 v[40:43], v14, s[10:11] offset:1024 nt
	global_load_dwordx4 v[44:47], v14, s[10:11] offset:2048 nt
	global_load_dwordx4 v[48:51], v14, s[10:11] offset:3072 nt
	s_lshl_b32 s6, s58, 12
	s_add_u32 s12, s48, s6
	s_addc_u32 s13, s49, 0
	s_add_u32 s12, s12, 0x26100800
	s_addc_u32 s13, s13, 0
	s_lshl_b32 s6, s58, 7
	s_add_u32 s14, s48, s6
	s_addc_u32 s15, s49, 0
	s_add_u32 s14, s14, 0x25e00000
	s_addc_u32 s15, s15, 0
	s_add_u32 s58, s58, s44
	s_lshl_b32 s6, s58, 13
	s_lshr_b32 s7, s58, 19
	s_add_u32 s10, s64, s6
	s_addc_u32 s11, s65, s7
	s_add_u32 s10, s10, 0x1000
	s_addc_u32 s11, s11, 0
	global_load_dwordx4 v[52:55], v14, s[10:11] offset:-4096 nt
	global_load_dwordx4 v[56:59], v14, s[10:11] offset:-3072 nt
	global_load_dwordx4 v[60:63], v14, s[10:11] offset:-2048 nt
	global_load_dwordx4 v[64:67], v14, s[10:11] offset:-1024 nt
	global_load_dwordx4 v[68:71], v14, s[10:11] offset:0 nt
	global_load_dwordx4 v[72:75], v14, s[10:11] offset:1024 nt
	global_load_dwordx4 v[76:79], v14, s[10:11] offset:2048 nt
	global_load_dwordx4 v[80:83], v14, s[10:11] offset:3072 nt
	s_waitcnt vmcnt(8)
; __device__ __forceinline__ unsigned pk2(float lo, float hi) { return pg8::cvt_pk_bf16(lo, hi); }
; __device__ __forceinline__ void xcvt_pass(const Ctx& C, const float* X, bf16* XB) {
;     ...
;     for (int m = gw; m < M; m += NGW) {
;         const f32x4* xr = (const f32x4*)(X + (size_t)m * D) + C.lane; v2u* o = (v2u*)(XB + (size_t)m * D) + C.lane; float s = 0.f;
; #pragma unroll
;         for (int j = 0; j < 8; ++j) { const f32x4 v = __builtin_nontemporal_load(xr + 64 * j); const v2u w = (v2u){pk2(v[0], v[1]), pk2(v[2], v[3])}; o[64 * j] = w;
;             const float x0 = __uint_as_float(w.x << 16), x1 = __uint_as_float(w.x & 0xffff0000u), x2 = __uint_as_float(w.y << 16), x3 = __uint_as_float(w.y & 0xffff0000u);
;             s += (x0 * x0 + x1 * x1) + (x2 * x2 + x3 * x3); }
;         s = wave_sum(s);
;         if (C.lane < 32) SS[(size_t)m * 32 + C.lane] = C.lane == 0 ? s : 0.f;
;     }
	v_cvt_pk_bf16_f32 v84, v20, v21
	v_cvt_pk_bf16_f32 v85, v22, v23
	global_store_dwordx2 v15, v[84:85], s[12:13] offset:-2048 sc0 sc1
	v_lshlrev_b32_e32 v20, 16, v84
	v_and_b32_e32 v21, 0xffff0000, v84
	v_lshlrev_b32_e32 v22, 16, v85
	v_and_b32_e32 v23, 0xffff0000, v85
	v_mul_f32_e32 v21, v21, v21
	v_mul_f32_e32 v23, v23, v23
	v_fmac_f32_e32 v21, v20, v20
	v_fmac_f32_e32 v23, v22, v22
	v_add_f32_e32 v17, v21, v23
	v_cvt_pk_bf16_f32 v86, v24, v25
	v_cvt_pk_bf16_f32 v87, v26, v27
	global_store_dwordx2 v15, v[86:87], s[12:13] offset:-1536 sc0 sc1
	v_lshlrev_b32_e32 v24, 16, v86
	v_and_b32_e32 v25, 0xffff0000, v86
	v_lshlrev_b32_e32 v26, 16, v87
	v_and_b32_e32 v27, 0xffff0000, v87
	v_mul_f32_e32 v25, v25, v25
	v_mul_f32_e32 v27, v27, v27
	v_fmac_f32_e32 v25, v24, v24
	v_fmac_f32_e32 v27, v26, v26
	v_add_f32_e32 v25, v25, v27
	v_add_f32_e32 v17, v17, v25
	v_cvt_pk_bf16_f32 v88, v28, v29
	v_cvt_pk_bf16_f32 v89, v30, v31
	global_store_dwordx2 v15, v[88:89], s[12:13] offset:-1024 sc0 sc1
	v_lshlrev_b32_e32 v28, 16, v88
	v_and_b32_e32 v29, 0xffff0000, v88
	v_lshlrev_b32_e32 v30, 16, v89
	v_and_b32_e32 v31, 0xffff0000, v89
	v_mul_f32_e32 v29, v29, v29
	v_mul_f32_e32 v31, v31, v31
	v_fmac_f32_e32 v29, v28, v28
	v_fmac_f32_e32 v31, v30, v30
	v_add_f32_e32 v29, v29, v31
	v_add_f32_e32 v17, v17, v29
	v_cvt_pk_bf16_f32 v90, v32, v33
	v_cvt_pk_bf16_f32 v91, v34, v35
	global_store_dwordx2 v15, v[90:91], s[12:13] offset:-512 sc0 sc1
	v_lshlrev_b32_e32 v32, 16, v90
	v_and_b32_e32 v33, 0xffff0000, v90
	v_lshlrev_b32_e32 v34, 16, v91
	v_and_b32_e32 v35, 0xffff0000, v91
	v_mul_f32_e32 v33, v33, v33
	v_mul_f32_e32 v35, v35, v35
	v_fmac_f32_e32 v33, v32, v32
	v_fmac_f32_e32 v35, v34, v34
	v_add_f32_e32 v33, v33, v35
	v_add_f32_e32 v17, v17, v33
	v_cvt_pk_bf16_f32 v92, v36, v37
	v_cvt_pk_bf16_f32 v93, v38, v39
	global_store_dwordx2 v15, v[92:93], s[12:13] offset:0 sc0 sc1
	v_lshlrev_b32_e32 v36, 16, v92
	v_and_b32_e32 v37, 0xffff0000, v92
	v_lshlrev_b32_e32 v38, 16, v93
	v_and_b32_e32 v39, 0xffff0000, v93
	v_mul_f32_e32 v37, v37, v37
	v_mul_f32_e32 v39, v39, v39
	v_fmac_f32_e32 v37, v36, v36
	v_fmac_f32_e32 v39, v38, v38
	v_add_f32_e32 v37, v37, v39
	v_add_f32_e32 v17, v17, v37
	v_cvt_pk_bf16_f32 v94, v40, v41
	v_cvt_pk_bf16_f32 v95, v42, v43
	global_store_dwordx2 v15, v[94:95], s[12:13] offset:512 sc0 sc1
	v_lshlrev_b32_e32 v40, 16, v94
	v_and_b32_e32 v41, 0xffff0000, v94
	v_lshlrev_b32_e32 v42, 16, v95
	v_and_b32_e32 v43, 0xffff0000, v95
	v_mul_f32_e32 v41, v41, v41
	v_mul_f32_e32 v43, v43, v43
	v_fmac_f32_e32 v41, v40, v40
	v_fmac_f32_e32 v43, v42, v42
	v_add_f32_e32 v41, v41, v43
	v_add_f32_e32 v17, v17, v41
	v_cvt_pk_bf16_f32 v96, v44, v45
	v_cvt_pk_bf16_f32 v97, v46, v47
	global_store_dwordx2 v15, v[96:97], s[12:13] offset:1024 sc0 sc1
	v_lshlrev_b32_e32 v44, 16, v96
	v_and_b32_e32 v45, 0xffff0000, v96
	v_lshlrev_b32_e32 v46, 16, v97
	v_and_b32_e32 v47, 0xffff0000, v97
	v_mul_f32_e32 v45, v45, v45
	v_mul_f32_e32 v47, v47, v47
	v_fmac_f32_e32 v45, v44, v44
	v_fmac_f32_e32 v47, v46, v46
	v_add_f32_e32 v45, v45, v47
	v_add_f32_e32 v17, v17, v45
	v_cvt_pk_bf16_f32 v98, v48, v49
	v_cvt_pk_bf16_f32 v99, v50, v51
	global_store_dwordx2 v15, v[98:99], s[12:13] offset:1536 sc0 sc1
	v_lshlrev_b32_e32 v48, 16, v98
	v_and_b32_e32 v49, 0xffff0000, v98
	v_lshlrev_b32_e32 v50, 16, v99
	v_and_b32_e32 v51, 0xffff0000, v99
	v_mul_f32_e32 v49, v49, v49
	v_mul_f32_e32 v51, v51, v51
	v_fmac_f32_e32 v49, v48, v48
	v_fmac_f32_e32 v51, v50, v50
	v_add_f32_e32 v49, v49, v51
	v_add_f32_e32 v17, v17, v49
	ds_bpermute_b32 v18, v120, v17
	s_waitcnt lgkmcnt(0)
	v_add_f32_e32 v17, v17, v18
	ds_bpermute_b32 v18, v121, v17
	s_waitcnt lgkmcnt(0)
	v_add_f32_e32 v17, v17, v18
	ds_bpermute_b32 v18, v122, v17
	s_waitcnt lgkmcnt(0)
	v_add_f32_e32 v17, v17, v18
	ds_bpermute_b32 v18, v123, v17
	s_waitcnt lgkmcnt(0)
	v_add_f32_e32 v17, v17, v18
	ds_bpermute_b32 v18, v124, v17
	s_waitcnt lgkmcnt(0)
	v_add_f32_e32 v17, v17, v18
	ds_bpermute_b32 v18, v125, v17
	s_waitcnt lgkmcnt(0)
	v_add_f32_e32 v17, v17, v18
	v_cmp_eq_u32_e32 vcc, 0, v1
	s_nop 1
	v_cndmask_b32_e32 v19, 0, v17, vcc
	s_mov_b64 s[8:9], exec
	s_mov_b32 exec_lo, -1
	s_mov_b32 exec_hi, 0
	global_store_dword v16, v19, s[14:15]
	s_mov_b64 exec, s[8:9]
	s_lshl_b32 s6, s58, 12
	s_add_u32 s12, s48, s6
	s_addc_u32 s13, s49, 0
	s_add_u32 s12, s12, 0x26100800
	s_addc_u32 s13, s13, 0
	s_lshl_b32 s6, s58, 7
	s_add_u32 s14, s48, s6
	s_addc_u32 s15, s49, 0
	s_add_u32 s14, s14, 0x25e00000
	s_addc_u32 s15, s15, 0
	s_add_u32 s58, s58, s44
	s_lshl_b32 s6, s58, 13
	s_lshr_b32 s7, s58, 19
	s_add_u32 s10, s64, s6
	s_addc_u32 s11, s65, s7
	s_add_u32 s10, s10, 0x1000
	s_addc_u32 s11, s11, 0
	global_load_dwordx4 v[20:23], v14, s[10:11] offset:-4096 nt
	global_load_dwordx4 v[24:27], v14, s[10:11] offset:-3072 nt
	global_load_dwordx4 v[28:31], v14, s[10:11] offset:-2048 nt
	global_load_dwordx4 v[32:35], v14, s[10:11] offset:-1024 nt
	global_load_dwordx4 v[36:39], v14, s[10:11] offset:0 nt
	global_load_dwordx4 v[40:43], v14, s[10:11] offset:1024 nt
	global_load_dwordx4 v[44:47], v14, s[10:11] offset:2048 nt
	global_load_dwordx4 v[48:51], v14, s[10:11] offset:3072 nt
	s_waitcnt vmcnt(17)
; __device__ __forceinline__ unsigned pk2(float lo, float hi) { return pg8::cvt_pk_bf16(lo, hi); }
; __device__ __forceinline__ void xcvt_pass(const Ctx& C, const float* X, bf16* XB) {
;     ...
;     for (int m = gw; m < M; m += NGW) {
;         const f32x4* xr = (const f32x4*)(X + (size_t)m * D) + C.lane; v2u* o = (v2u*)(XB + (size_t)m * D) + C.lane; float s = 0.f;
; #pragma unroll
;         for (int j = 0; j < 8; ++j) { const f32x4 v = __builtin_nontemporal_load(xr + 64 * j); const v2u w = (v2u){pk2(v[0], v[1]), pk2(v[2], v[3])}; o[64 * j] = w;
;             const float x0 = __uint_as_float(w.x << 16), x1 = __uint_as_float(w.x & 0xffff0000u), x2 = __uint_as_float(w.y << 16), x3 = __uint_as_float(w.y & 0xffff0000u);
;             s += (x0 * x0 + x1 * x1) + (x2 * x2 + x3 * x3); }
;         s = wave_sum(s);
;         if (C.lane < 32) SS[(size_t)m * 32 + C.lane] = C.lane == 0 ? s : 0.f;
;     }
	v_cvt_pk_bf16_f32 v100, v52, v53
	v_cvt_pk_bf16_f32 v101, v54, v55
	global_store_dwordx2 v15, v[100:101], s[12:13] offset:-2048 sc0 sc1
	v_lshlrev_b32_e32 v52, 16, v100
	v_and_b32_e32 v53, 0xffff0000, v100
	v_lshlrev_b32_e32 v54, 16, v101
	v_and_b32_e32 v55, 0xffff0000, v101
	v_mul_f32_e32 v53, v53, v53
	v_mul_f32_e32 v55, v55, v55
	v_fmac_f32_e32 v53, v52, v52
	v_fmac_f32_e32 v55, v54, v54
	v_add_f32_e32 v17, v53, v55
	v_cvt_pk_bf16_f32 v102, v56, v57
	v_cvt_pk_bf16_f32 v103, v58, v59
	global_store_dwordx2 v15, v[102:103], s[12:13] offset:-1536 sc0 sc1
	v_lshlrev_b32_e32 v56, 16, v102
	v_and_b32_e32 v57, 0xffff0000, v102
	v_lshlrev_b32_e32 v58, 16, v103
	v_and_b32_e32 v59, 0xffff0000, v103
	v_mul_f32_e32 v57, v57, v57
	v_mul_f32_e32 v59, v59, v59
	v_fmac_f32_e32 v57, v56, v56
	v_fmac_f32_e32 v59, v58, v58
	v_add_f32_e32 v57, v57, v59
	v_add_f32_e32 v17, v17, v57
	v_cvt_pk_bf16_f32 v104, v60, v61
	v_cvt_pk_bf16_f32 v105, v62, v63
	global_store_dwordx2 v15, v[104:105], s[12:13] offset:-1024 sc0 sc1
	v_lshlrev_b32_e32 v60, 16, v104
	v_and_b32_e32 v61, 0xffff0000, v104
	v_lshlrev_b32_e32 v62, 16, v105
	v_and_b32_e32 v63, 0xffff0000, v105
	v_mul_f32_e32 v61, v61, v61
	v_mul_f32_e32 v63, v63, v63
	v_fmac_f32_e32 v61, v60, v60
	v_fmac_f32_e32 v63, v62, v62
	v_add_f32_e32 v61, v61, v63
	v_add_f32_e32 v17, v17, v61
	v_cvt_pk_bf16_f32 v106, v64, v65
	v_cvt_pk_bf16_f32 v107, v66, v67
	global_store_dwordx2 v15, v[106:107], s[12:13] offset:-512 sc0 sc1
	v_lshlrev_b32_e32 v64, 16, v106
	v_and_b32_e32 v65, 0xffff0000, v106
	v_lshlrev_b32_e32 v66, 16, v107
	v_and_b32_e32 v67, 0xffff0000, v107
	v_mul_f32_e32 v65, v65, v65
	v_mul_f32_e32 v67, v67, v67
	v_fmac_f32_e32 v65, v64, v64
	v_fmac_f32_e32 v67, v66, v66
	v_add_f32_e32 v65, v65, v67
	v_add_f32_e32 v17, v17, v65
	v_cvt_pk_bf16_f32 v108, v68, v69
	v_cvt_pk_bf16_f32 v109, v70, v71
	global_store_dwordx2 v15, v[108:109], s[12:13] offset:0 sc0 sc1
	v_lshlrev_b32_e32 v68, 16, v108
	v_and_b32_e32 v69, 0xffff0000, v108
	v_lshlrev_b32_e32 v70, 16, v109
	v_and_b32_e32 v71, 0xffff0000, v109
	v_mul_f32_e32 v69, v69, v69
	v_mul_f32_e32 v71, v71, v71
	v_fmac_f32_e32 v69, v68, v68
	v_fmac_f32_e32 v71, v70, v70
	v_add_f32_e32 v69, v69, v71
	v_add_f32_e32 v17, v17, v69
	v_cvt_pk_bf16_f32 v110, v72, v73
	v_cvt_pk_bf16_f32 v111, v74, v75
	global_store_dwordx2 v15, v[110:111], s[12:13] offset:512 sc0 sc1
	v_lshlrev_b32_e32 v72, 16, v110
	v_and_b32_e32 v73, 0xffff0000, v110
	v_lshlrev_b32_e32 v74, 16, v111
	v_and_b32_e32 v75, 0xffff0000, v111
	v_mul_f32_e32 v73, v73, v73
	v_mul_f32_e32 v75, v75, v75
	v_fmac_f32_e32 v73, v72, v72
	v_fmac_f32_e32 v75, v74, v74
	v_add_f32_e32 v73, v73, v75
	v_add_f32_e32 v17, v17, v73
	v_cvt_pk_bf16_f32 v112, v76, v77
	v_cvt_pk_bf16_f32 v113, v78, v79
	global_store_dwordx2 v15, v[112:113], s[12:13] offset:1024 sc0 sc1
	v_lshlrev_b32_e32 v76, 16, v112
	v_and_b32_e32 v77, 0xffff0000, v112
	v_lshlrev_b32_e32 v78, 16, v113
	v_and_b32_e32 v79, 0xffff0000, v113
	v_mul_f32_e32 v77, v77, v77
	v_mul_f32_e32 v79, v79, v79
	v_fmac_f32_e32 v77, v76, v76
	v_fmac_f32_e32 v79, v78, v78
	v_add_f32_e32 v77, v77, v79
	v_add_f32_e32 v17, v17, v77
	v_cvt_pk_bf16_f32 v114, v80, v81
	v_cvt_pk_bf16_f32 v115, v82, v83
	global_store_dwordx2 v15, v[114:115], s[12:13] offset:1536 sc0 sc1
	v_lshlrev_b32_e32 v80, 16, v114
	v_and_b32_e32 v81, 0xffff0000, v114
	v_lshlrev_b32_e32 v82, 16, v115
	v_and_b32_e32 v83, 0xffff0000, v115
	v_mul_f32_e32 v81, v81, v81
	v_mul_f32_e32 v83, v83, v83
	v_fmac_f32_e32 v81, v80, v80
	v_fmac_f32_e32 v83, v82, v82
	v_add_f32_e32 v81, v81, v83
	v_add_f32_e32 v17, v17, v81
	ds_bpermute_b32 v18, v120, v17
	s_waitcnt lgkmcnt(0)
	v_add_f32_e32 v17, v17, v18
	ds_bpermute_b32 v18, v121, v17
	s_waitcnt lgkmcnt(0)
	v_add_f32_e32 v17, v17, v18
	ds_bpermute_b32 v18, v122, v17
	s_waitcnt lgkmcnt(0)
	v_add_f32_e32 v17, v17, v18
	ds_bpermute_b32 v18, v123, v17
	s_waitcnt lgkmcnt(0)
	v_add_f32_e32 v17, v17, v18
	ds_bpermute_b32 v18, v124, v17
	s_waitcnt lgkmcnt(0)
	v_add_f32_e32 v17, v17, v18
	ds_bpermute_b32 v18, v125, v17
	s_waitcnt lgkmcnt(0)
	v_add_f32_e32 v17, v17, v18
	v_cmp_eq_u32_e32 vcc, 0, v1
	s_nop 1
	v_cndmask_b32_e32 v19, 0, v17, vcc
	s_mov_b64 s[8:9], exec
	s_mov_b32 exec_lo, -1
	s_mov_b32 exec_hi, 0
	global_store_dword v16, v19, s[14:15]
	s_mov_b64 exec, s[8:9]
	s_lshl_b32 s6, s58, 12
	s_add_u32 s12, s48, s6
	s_addc_u32 s13, s49, 0
	s_add_u32 s12, s12, 0x26100800
	s_addc_u32 s13, s13, 0
	s_lshl_b32 s6, s58, 7
	s_add_u32 s14, s48, s6
	s_addc_u32 s15, s49, 0
	s_add_u32 s14, s14, 0x25e00000
	s_addc_u32 s15, s15, 0
	s_add_u32 s58, s58, s44
	s_lshl_b32 s6, s58, 13
	s_lshr_b32 s7, s58, 19
	s_add_u32 s10, s64, s6
	s_addc_u32 s11, s65, s7
	s_add_u32 s10, s10, 0x1000
	s_addc_u32 s11, s11, 0
	global_load_dwordx4 v[52:55], v14, s[10:11] offset:-4096 nt
	global_load_dwordx4 v[56:59], v14, s[10:11] offset:-3072 nt
	global_load_dwordx4 v[60:63], v14, s[10:11] offset:-2048 nt
	global_load_dwordx4 v[64:67], v14, s[10:11] offset:-1024 nt
	global_load_dwordx4 v[68:71], v14, s[10:11] offset:0 nt
	global_load_dwordx4 v[72:75], v14, s[10:11] offset:1024 nt
	global_load_dwordx4 v[76:79], v14, s[10:11] offset:2048 nt
	global_load_dwordx4 v[80:83], v14, s[10:11] offset:3072 nt
	s_waitcnt vmcnt(17)
; __device__ __forceinline__ unsigned pk2(float lo, float hi) { return pg8::cvt_pk_bf16(lo, hi); }
; __device__ __forceinline__ void xcvt_pass(const Ctx& C, const float* X, bf16* XB) {
;     ...
;     for (int m = gw; m < M; m += NGW) {
;         const f32x4* xr = (const f32x4*)(X + (size_t)m * D) + C.lane; v2u* o = (v2u*)(XB + (size_t)m * D) + C.lane; float s = 0.f;
; #pragma unroll
;         for (int j = 0; j < 8; ++j) { const f32x4 v = __builtin_nontemporal_load(xr + 64 * j); const v2u w = (v2u){pk2(v[0], v[1]), pk2(v[2], v[3])}; o[64 * j] = w;
;             const float x0 = __uint_as_float(w.x << 16), x1 = __uint_as_float(w.x & 0xffff0000u), x2 = __uint_as_float(w.y << 16), x3 = __uint_as_float(w.y & 0xffff0000u);
;             s += (x0 * x0 + x1 * x1) + (x2 * x2 + x3 * x3); }
;         s = wave_sum(s);
;         if (C.lane < 32) SS[(size_t)m * 32 + C.lane] = C.lane == 0 ? s : 0.f;
;     }
	v_cvt_pk_bf16_f32 v84, v20, v21
	v_cvt_pk_bf16_f32 v85, v22, v23
	global_store_dwordx2 v15, v[84:85], s[12:13] offset:-2048 sc0 sc1
	v_lshlrev_b32_e32 v20, 16, v84
	v_and_b32_e32 v21, 0xffff0000, v84
	v_lshlrev_b32_e32 v22, 16, v85
	v_and_b32_e32 v23, 0xffff0000, v85
	v_mul_f32_e32 v21, v21, v21
	v_mul_f32_e32 v23, v23, v23
	v_fmac_f32_e32 v21, v20, v20
	v_fmac_f32_e32 v23, v22, v22
	v_add_f32_e32 v17, v21, v23
	v_cvt_pk_bf16_f32 v86, v24, v25
	v_cvt_pk_bf16_f32 v87, v26, v27
	global_store_dwordx2 v15, v[86:87], s[12:13] offset:-1536 sc0 sc1
	v_lshlrev_b32_e32 v24, 16, v86
	v_and_b32_e32 v25, 0xffff0000, v86
	v_lshlrev_b32_e32 v26, 16, v87
	v_and_b32_e32 v27, 0xffff0000, v87
	v_mul_f32_e32 v25, v25, v25
	v_mul_f32_e32 v27, v27, v27
	v_fmac_f32_e32 v25, v24, v24
	v_fmac_f32_e32 v27, v26, v26
	v_add_f32_e32 v25, v25, v27
	v_add_f32_e32 v17, v17, v25
	v_cvt_pk_bf16_f32 v88, v28, v29
	v_cvt_pk_bf16_f32 v89, v30, v31
	global_store_dwordx2 v15, v[88:89], s[12:13] offset:-1024 sc0 sc1
	v_lshlrev_b32_e32 v28, 16, v88
	v_and_b32_e32 v29, 0xffff0000, v88
	v_lshlrev_b32_e32 v30, 16, v89
	v_and_b32_e32 v31, 0xffff0000, v89
	v_mul_f32_e32 v29, v29, v29
	v_mul_f32_e32 v31, v31, v31
	v_fmac_f32_e32 v29, v28, v28
	v_fmac_f32_e32 v31, v30, v30
	v_add_f32_e32 v29, v29, v31
	v_add_f32_e32 v17, v17, v29
	v_cvt_pk_bf16_f32 v90, v32, v33
	v_cvt_pk_bf16_f32 v91, v34, v35
	global_store_dwordx2 v15, v[90:91], s[12:13] offset:-512 sc0 sc1
	v_lshlrev_b32_e32 v32, 16, v90
	v_and_b32_e32 v33, 0xffff0000, v90
	v_lshlrev_b32_e32 v34, 16, v91
	v_and_b32_e32 v35, 0xffff0000, v91
	v_mul_f32_e32 v33, v33, v33
	v_mul_f32_e32 v35, v35, v35
	v_fmac_f32_e32 v33, v32, v32
	v_fmac_f32_e32 v35, v34, v34
	v_add_f32_e32 v33, v33, v35
	v_add_f32_e32 v17, v17, v33
	v_cvt_pk_bf16_f32 v92, v36, v37
	v_cvt_pk_bf16_f32 v93, v38, v39
	global_store_dwordx2 v15, v[92:93], s[12:13] offset:0 sc0 sc1
	v_lshlrev_b32_e32 v36, 16, v92
	v_and_b32_e32 v37, 0xffff0000, v92
	v_lshlrev_b32_e32 v38, 16, v93
	v_and_b32_e32 v39, 0xffff0000, v93
	v_mul_f32_e32 v37, v37, v37
	v_mul_f32_e32 v39, v39, v39
	v_fmac_f32_e32 v37, v36, v36
	v_fmac_f32_e32 v39, v38, v38
	v_add_f32_e32 v37, v37, v39
	v_add_f32_e32 v17, v17, v37
	v_cvt_pk_bf16_f32 v94, v40, v41
	v_cvt_pk_bf16_f32 v95, v42, v43
	global_store_dwordx2 v15, v[94:95], s[12:13] offset:512 sc0 sc1
	v_lshlrev_b32_e32 v40, 16, v94
	v_and_b32_e32 v41, 0xffff0000, v94
	v_lshlrev_b32_e32 v42, 16, v95
	v_and_b32_e32 v43, 0xffff0000, v95
	v_mul_f32_e32 v41, v41, v41
	v_mul_f32_e32 v43, v43, v43
	v_fmac_f32_e32 v41, v40, v40
	v_fmac_f32_e32 v43, v42, v42
	v_add_f32_e32 v41, v41, v43
	v_add_f32_e32 v17, v17, v41
	v_cvt_pk_bf16_f32 v96, v44, v45
	v_cvt_pk_bf16_f32 v97, v46, v47
	global_store_dwordx2 v15, v[96:97], s[12:13] offset:1024 sc0 sc1
	v_lshlrev_b32_e32 v44, 16, v96
	v_and_b32_e32 v45, 0xffff0000, v96
	v_lshlrev_b32_e32 v46, 16, v97
	v_and_b32_e32 v47, 0xffff0000, v97
	v_mul_f32_e32 v45, v45, v45
	v_mul_f32_e32 v47, v47, v47
	v_fmac_f32_e32 v45, v44, v44
	v_fmac_f32_e32 v47, v46, v46
	v_add_f32_e32 v45, v45, v47
	v_add_f32_e32 v17, v17, v45
	v_cvt_pk_bf16_f32 v98, v48, v49
	v_cvt_pk_bf16_f32 v99, v50, v51
	global_store_dwordx2 v15, v[98:99], s[12:13] offset:1536 sc0 sc1
	v_lshlrev_b32_e32 v48, 16, v98
	v_and_b32_e32 v49, 0xffff0000, v98
	v_lshlrev_b32_e32 v50, 16, v99
	v_and_b32_e32 v51, 0xffff0000, v99
	v_mul_f32_e32 v49, v49, v49
	v_mul_f32_e32 v51, v51, v51
	v_fmac_f32_e32 v49, v48, v48
	v_fmac_f32_e32 v51, v50, v50
	v_add_f32_e32 v49, v49, v51
	v_add_f32_e32 v17, v17, v49
	ds_bpermute_b32 v18, v120, v17
	s_waitcnt lgkmcnt(0)
	v_add_f32_e32 v17, v17, v18
	ds_bpermute_b32 v18, v121, v17
	s_waitcnt lgkmcnt(0)
	v_add_f32_e32 v17, v17, v18
	ds_bpermute_b32 v18, v122, v17
	s_waitcnt lgkmcnt(0)
	v_add_f32_e32 v17, v17, v18
	ds_bpermute_b32 v18, v123, v17
	s_waitcnt lgkmcnt(0)
	v_add_f32_e32 v17, v17, v18
	ds_bpermute_b32 v18, v124, v17
	s_waitcnt lgkmcnt(0)
	v_add_f32_e32 v17, v17, v18
	ds_bpermute_b32 v18, v125, v17
	s_waitcnt lgkmcnt(0)
	v_add_f32_e32 v17, v17, v18
	v_cmp_eq_u32_e32 vcc, 0, v1
	s_nop 1
	v_cndmask_b32_e32 v19, 0, v17, vcc
	s_mov_b64 s[8:9], exec
	s_mov_b32 exec_lo, -1
	s_mov_b32 exec_hi, 0
	global_store_dword v16, v19, s[14:15]
	s_mov_b64 exec, s[8:9]
	s_lshl_b32 s6, s58, 12
	s_add_u32 s12, s48, s6
	s_addc_u32 s13, s49, 0
	s_add_u32 s12, s12, 0x26100800
	s_addc_u32 s13, s13, 0
	s_lshl_b32 s6, s58, 7
	s_add_u32 s14, s48, s6
	s_addc_u32 s15, s49, 0
	s_add_u32 s14, s14, 0x25e00000
	s_addc_u32 s15, s15, 0
	s_add_u32 s58, s58, s44
	s_lshl_b32 s6, s58, 13
	s_lshr_b32 s7, s58, 19
	s_add_u32 s10, s64, s6
	s_addc_u32 s11, s65, s7
	s_add_u32 s10, s10, 0x1000
	s_addc_u32 s11, s11, 0
	global_load_dwordx4 v[20:23], v14, s[10:11] offset:-4096 nt
	global_load_dwordx4 v[24:27], v14, s[10:11] offset:-3072 nt
	global_load_dwordx4 v[28:31], v14, s[10:11] offset:-2048 nt
	global_load_dwordx4 v[32:35], v14, s[10:11] offset:-1024 nt
	global_load_dwordx4 v[36:39], v14, s[10:11] offset:0 nt
	global_load_dwordx4 v[40:43], v14, s[10:11] offset:1024 nt
	global_load_dwordx4 v[44:47], v14, s[10:11] offset:2048 nt
	global_load_dwordx4 v[48:51], v14, s[10:11] offset:3072 nt
	s_waitcnt vmcnt(17)
; __device__ __forceinline__ unsigned pk2(float lo, float hi) { return pg8::cvt_pk_bf16(lo, hi); }
; __device__ __forceinline__ void xcvt_pass(const Ctx& C, const float* X, bf16* XB) {
;     ...
;     for (int m = gw; m < M; m += NGW) {
;         const f32x4* xr = (const f32x4*)(X + (size_t)m * D) + C.lane; v2u* o = (v2u*)(XB + (size_t)m * D) + C.lane; float s = 0.f;
; #pragma unroll
;         for (int j = 0; j < 8; ++j) { const f32x4 v = __builtin_nontemporal_load(xr + 64 * j); const v2u w = (v2u){pk2(v[0], v[1]), pk2(v[2], v[3])}; o[64 * j] = w;
;             const float x0 = __uint_as_float(w.x << 16), x1 = __uint_as_float(w.x & 0xffff0000u), x2 = __uint_as_float(w.y << 16), x3 = __uint_as_float(w.y & 0xffff0000u);
;             s += (x0 * x0 + x1 * x1) + (x2 * x2 + x3 * x3); }
;         s = wave_sum(s);
;         if (C.lane < 32) SS[(size_t)m * 32 + C.lane] = C.lane == 0 ? s : 0.f;
;     }
	v_cvt_pk_bf16_f32 v100, v52, v53
	v_cvt_pk_bf16_f32 v101, v54, v55
	global_store_dwordx2 v15, v[100:101], s[12:13] offset:-2048 sc0 sc1
	v_lshlrev_b32_e32 v52, 16, v100
	v_and_b32_e32 v53, 0xffff0000, v100
	v_lshlrev_b32_e32 v54, 16, v101
	v_and_b32_e32 v55, 0xffff0000, v101
	v_mul_f32_e32 v53, v53, v53
	v_mul_f32_e32 v55, v55, v55
	v_fmac_f32_e32 v53, v52, v52
	v_fmac_f32_e32 v55, v54, v54
	v_add_f32_e32 v17, v53, v55
	v_cvt_pk_bf16_f32 v102, v56, v57
	v_cvt_pk_bf16_f32 v103, v58, v59
	global_store_dwordx2 v15, v[102:103], s[12:13] offset:-1536 sc0 sc1
	v_lshlrev_b32_e32 v56, 16, v102
	v_and_b32_e32 v57, 0xffff0000, v102
	v_lshlrev_b32_e32 v58, 16, v103
	v_and_b32_e32 v59, 0xffff0000, v103
	v_mul_f32_e32 v57, v57, v57
	v_mul_f32_e32 v59, v59, v59
	v_fmac_f32_e32 v57, v56, v56
	v_fmac_f32_e32 v59, v58, v58
	v_add_f32_e32 v57, v57, v59
	v_add_f32_e32 v17, v17, v57
	v_cvt_pk_bf16_f32 v104, v60, v61
	v_cvt_pk_bf16_f32 v105, v62, v63
	global_store_dwordx2 v15, v[104:105], s[12:13] offset:-1024 sc0 sc1
	v_lshlrev_b32_e32 v60, 16, v104
	v_and_b32_e32 v61, 0xffff0000, v104
	v_lshlrev_b32_e32 v62, 16, v105
	v_and_b32_e32 v63, 0xffff0000, v105
	v_mul_f32_e32 v61, v61, v61
	v_mul_f32_e32 v63, v63, v63
	v_fmac_f32_e32 v61, v60, v60
	v_fmac_f32_e32 v63, v62, v62
	v_add_f32_e32 v61, v61, v63
	v_add_f32_e32 v17, v17, v61
	v_cvt_pk_bf16_f32 v106, v64, v65
	v_cvt_pk_bf16_f32 v107, v66, v67
	global_store_dwordx2 v15, v[106:107], s[12:13] offset:-512 sc0 sc1
	v_lshlrev_b32_e32 v64, 16, v106
	v_and_b32_e32 v65, 0xffff0000, v106
	v_lshlrev_b32_e32 v66, 16, v107
	v_and_b32_e32 v67, 0xffff0000, v107
	v_mul_f32_e32 v65, v65, v65
	v_mul_f32_e32 v67, v67, v67
	v_fmac_f32_e32 v65, v64, v64
	v_fmac_f32_e32 v67, v66, v66
	v_add_f32_e32 v65, v65, v67
	v_add_f32_e32 v17, v17, v65
	v_cvt_pk_bf16_f32 v108, v68, v69
	v_cvt_pk_bf16_f32 v109, v70, v71
	global_store_dwordx2 v15, v[108:109], s[12:13] offset:0 sc0 sc1
	v_lshlrev_b32_e32 v68, 16, v108
	v_and_b32_e32 v69, 0xffff0000, v108
	v_lshlrev_b32_e32 v70, 16, v109
	v_and_b32_e32 v71, 0xffff0000, v109
	v_mul_f32_e32 v69, v69, v69
	v_mul_f32_e32 v71, v71, v71
	v_fmac_f32_e32 v69, v68, v68
	v_fmac_f32_e32 v71, v70, v70
	v_add_f32_e32 v69, v69, v71
	v_add_f32_e32 v17, v17, v69
	v_cvt_pk_bf16_f32 v110, v72, v73
	v_cvt_pk_bf16_f32 v111, v74, v75
	global_store_dwordx2 v15, v[110:111], s[12:13] offset:512 sc0 sc1
	v_lshlrev_b32_e32 v72, 16, v110
	v_and_b32_e32 v73, 0xffff0000, v110
	v_lshlrev_b32_e32 v74, 16, v111
	v_and_b32_e32 v75, 0xffff0000, v111
	v_mul_f32_e32 v73, v73, v73
	v_mul_f32_e32 v75, v75, v75
	v_fmac_f32_e32 v73, v72, v72
	v_fmac_f32_e32 v75, v74, v74
	v_add_f32_e32 v73, v73, v75
	v_add_f32_e32 v17, v17, v73
	v_cvt_pk_bf16_f32 v112, v76, v77
	v_cvt_pk_bf16_f32 v113, v78, v79
	global_store_dwordx2 v15, v[112:113], s[12:13] offset:1024 sc0 sc1
	v_lshlrev_b32_e32 v76, 16, v112
	v_and_b32_e32 v77, 0xffff0000, v112
	v_lshlrev_b32_e32 v78, 16, v113
	v_and_b32_e32 v79, 0xffff0000, v113
	v_mul_f32_e32 v77, v77, v77
	v_mul_f32_e32 v79, v79, v79
	v_fmac_f32_e32 v77, v76, v76
	v_fmac_f32_e32 v79, v78, v78
	v_add_f32_e32 v77, v77, v79
	v_add_f32_e32 v17, v17, v77
	v_cvt_pk_bf16_f32 v114, v80, v81
	v_cvt_pk_bf16_f32 v115, v82, v83
	global_store_dwordx2 v15, v[114:115], s[12:13] offset:1536 sc0 sc1
	v_lshlrev_b32_e32 v80, 16, v114
	v_and_b32_e32 v81, 0xffff0000, v114
	v_lshlrev_b32_e32 v82, 16, v115
	v_and_b32_e32 v83, 0xffff0000, v115
	v_mul_f32_e32 v81, v81, v81
	v_mul_f32_e32 v83, v83, v83
	v_fmac_f32_e32 v81, v80, v80
	v_fmac_f32_e32 v83, v82, v82
	v_add_f32_e32 v81, v81, v83
	v_add_f32_e32 v17, v17, v81
	ds_bpermute_b32 v18, v120, v17
	s_waitcnt lgkmcnt(0)
	v_add_f32_e32 v17, v17, v18
	ds_bpermute_b32 v18, v121, v17
	s_waitcnt lgkmcnt(0)
	v_add_f32_e32 v17, v17, v18
	ds_bpermute_b32 v18, v122, v17
	s_waitcnt lgkmcnt(0)
	v_add_f32_e32 v17, v17, v18
	ds_bpermute_b32 v18, v123, v17
	s_waitcnt lgkmcnt(0)
	v_add_f32_e32 v17, v17, v18
	ds_bpermute_b32 v18, v124, v17
	s_waitcnt lgkmcnt(0)
	v_add_f32_e32 v17, v17, v18
	ds_bpermute_b32 v18, v125, v17
	s_waitcnt lgkmcnt(0)
	v_add_f32_e32 v17, v17, v18
	v_cmp_eq_u32_e32 vcc, 0, v1
	s_nop 1
	v_cndmask_b32_e32 v19, 0, v17, vcc
	s_mov_b64 s[8:9], exec
	s_mov_b32 exec_lo, -1
	s_mov_b32 exec_hi, 0
	global_store_dword v16, v19, s[14:15]
	s_mov_b64 exec, s[8:9]
	s_lshl_b32 s6, s58, 12
	s_add_u32 s12, s48, s6
	s_addc_u32 s13, s49, 0
	s_add_u32 s12, s12, 0x26100800
	s_addc_u32 s13, s13, 0
	s_lshl_b32 s6, s58, 7
	s_add_u32 s14, s48, s6
	s_addc_u32 s15, s49, 0
	s_add_u32 s14, s14, 0x25e00000
	s_addc_u32 s15, s15, 0
	s_add_u32 s58, s58, s44
	s_lshl_b32 s6, s58, 13
	s_lshr_b32 s7, s58, 19
	s_add_u32 s10, s64, s6
	s_addc_u32 s11, s65, s7
	s_add_u32 s10, s10, 0x1000
	s_addc_u32 s11, s11, 0
	global_load_dwordx4 v[52:55], v14, s[10:11] offset:-4096 nt
	global_load_dwordx4 v[56:59], v14, s[10:11] offset:-3072 nt
	global_load_dwordx4 v[60:63], v14, s[10:11] offset:-2048 nt
	global_load_dwordx4 v[64:67], v14, s[10:11] offset:-1024 nt
	global_load_dwordx4 v[68:71], v14, s[10:11] offset:0 nt
	global_load_dwordx4 v[72:75], v14, s[10:11] offset:1024 nt
	global_load_dwordx4 v[76:79], v14, s[10:11] offset:2048 nt
	global_load_dwordx4 v[80:83], v14, s[10:11] offset:3072 nt
	s_waitcnt vmcnt(17)
; __device__ __forceinline__ unsigned pk2(float lo, float hi) { return pg8::cvt_pk_bf16(lo, hi); }
; __device__ __forceinline__ void xcvt_pass(const Ctx& C, const float* X, bf16* XB) {
;     ...
;     for (int m = gw; m < M; m += NGW) {
;         const f32x4* xr = (const f32x4*)(X + (size_t)m * D) + C.lane; v2u* o = (v2u*)(XB + (size_t)m * D) + C.lane; float s = 0.f;
; #pragma unroll
;         for (int j = 0; j < 8; ++j) { const f32x4 v = __builtin_nontemporal_load(xr + 64 * j); const v2u w = (v2u){pk2(v[0], v[1]), pk2(v[2], v[3])}; o[64 * j] = w;
;             const float x0 = __uint_as_float(w.x << 16), x1 = __uint_as_float(w.x & 0xffff0000u), x2 = __uint_as_float(w.y << 16), x3 = __uint_as_float(w.y & 0xffff0000u);
;             s += (x0 * x0 + x1 * x1) + (x2 * x2 + x3 * x3); }
;         s = wave_sum(s);
;         if (C.lane < 32) SS[(size_t)m * 32 + C.lane] = C.lane == 0 ? s : 0.f;
;     }
	v_cvt_pk_bf16_f32 v84, v20, v21
	v_cvt_pk_bf16_f32 v85, v22, v23
	global_store_dwordx2 v15, v[84:85], s[12:13] offset:-2048 sc0 sc1
	v_lshlrev_b32_e32 v20, 16, v84
	v_and_b32_e32 v21, 0xffff0000, v84
	v_lshlrev_b32_e32 v22, 16, v85
	v_and_b32_e32 v23, 0xffff0000, v85
	v_mul_f32_e32 v21, v21, v21
	v_mul_f32_e32 v23, v23, v23
	v_fmac_f32_e32 v21, v20, v20
	v_fmac_f32_e32 v23, v22, v22
	v_add_f32_e32 v17, v21, v23
	v_cvt_pk_bf16_f32 v86, v24, v25
	v_cvt_pk_bf16_f32 v87, v26, v27
	global_store_dwordx2 v15, v[86:87], s[12:13] offset:-1536 sc0 sc1
	v_lshlrev_b32_e32 v24, 16, v86
	v_and_b32_e32 v25, 0xffff0000, v86
	v_lshlrev_b32_e32 v26, 16, v87
	v_and_b32_e32 v27, 0xffff0000, v87
	v_mul_f32_e32 v25, v25, v25
	v_mul_f32_e32 v27, v27, v27
	v_fmac_f32_e32 v25, v24, v24
	v_fmac_f32_e32 v27, v26, v26
	v_add_f32_e32 v25, v25, v27
	v_add_f32_e32 v17, v17, v25
	v_cvt_pk_bf16_f32 v88, v28, v29
	v_cvt_pk_bf16_f32 v89, v30, v31
	global_store_dwordx2 v15, v[88:89], s[12:13] offset:-1024 sc0 sc1
	v_lshlrev_b32_e32 v28, 16, v88
	v_and_b32_e32 v29, 0xffff0000, v88
	v_lshlrev_b32_e32 v30, 16, v89
	v_and_b32_e32 v31, 0xffff0000, v89
	v_mul_f32_e32 v29, v29, v29
	v_mul_f32_e32 v31, v31, v31
	v_fmac_f32_e32 v29, v28, v28
	v_fmac_f32_e32 v31, v30, v30
	v_add_f32_e32 v29, v29, v31
	v_add_f32_e32 v17, v17, v29
	v_cvt_pk_bf16_f32 v90, v32, v33
	v_cvt_pk_bf16_f32 v91, v34, v35
	global_store_dwordx2 v15, v[90:91], s[12:13] offset:-512 sc0 sc1
	v_lshlrev_b32_e32 v32, 16, v90
	v_and_b32_e32 v33, 0xffff0000, v90
	v_lshlrev_b32_e32 v34, 16, v91
	v_and_b32_e32 v35, 0xffff0000, v91
	v_mul_f32_e32 v33, v33, v33
	v_mul_f32_e32 v35, v35, v35
	v_fmac_f32_e32 v33, v32, v32
	v_fmac_f32_e32 v35, v34, v34
	v_add_f32_e32 v33, v33, v35
	v_add_f32_e32 v17, v17, v33
	v_cvt_pk_bf16_f32 v92, v36, v37
	v_cvt_pk_bf16_f32 v93, v38, v39
	global_store_dwordx2 v15, v[92:93], s[12:13] offset:0 sc0 sc1
	v_lshlrev_b32_e32 v36, 16, v92
	v_and_b32_e32 v37, 0xffff0000, v92
	v_lshlrev_b32_e32 v38, 16, v93
	v_and_b32_e32 v39, 0xffff0000, v93
	v_mul_f32_e32 v37, v37, v37
	v_mul_f32_e32 v39, v39, v39
	v_fmac_f32_e32 v37, v36, v36
	v_fmac_f32_e32 v39, v38, v38
	v_add_f32_e32 v37, v37, v39
	v_add_f32_e32 v17, v17, v37
	v_cvt_pk_bf16_f32 v94, v40, v41
	v_cvt_pk_bf16_f32 v95, v42, v43
	global_store_dwordx2 v15, v[94:95], s[12:13] offset:512 sc0 sc1
	v_lshlrev_b32_e32 v40, 16, v94
	v_and_b32_e32 v41, 0xffff0000, v94
	v_lshlrev_b32_e32 v42, 16, v95
	v_and_b32_e32 v43, 0xffff0000, v95
	v_mul_f32_e32 v41, v41, v41
	v_mul_f32_e32 v43, v43, v43
	v_fmac_f32_e32 v41, v40, v40
	v_fmac_f32_e32 v43, v42, v42
	v_add_f32_e32 v41, v41, v43
	v_add_f32_e32 v17, v17, v41
	v_cvt_pk_bf16_f32 v96, v44, v45
	v_cvt_pk_bf16_f32 v97, v46, v47
	global_store_dwordx2 v15, v[96:97], s[12:13] offset:1024 sc0 sc1
	v_lshlrev_b32_e32 v44, 16, v96
	v_and_b32_e32 v45, 0xffff0000, v96
	v_lshlrev_b32_e32 v46, 16, v97
	v_and_b32_e32 v47, 0xffff0000, v97
	v_mul_f32_e32 v45, v45, v45
	v_mul_f32_e32 v47, v47, v47
	v_fmac_f32_e32 v45, v44, v44
	v_fmac_f32_e32 v47, v46, v46
	v_add_f32_e32 v45, v45, v47
	v_add_f32_e32 v17, v17, v45
	v_cvt_pk_bf16_f32 v98, v48, v49
	v_cvt_pk_bf16_f32 v99, v50, v51
	global_store_dwordx2 v15, v[98:99], s[12:13] offset:1536 sc0 sc1
	v_lshlrev_b32_e32 v48, 16, v98
	v_and_b32_e32 v49, 0xffff0000, v98
	v_lshlrev_b32_e32 v50, 16, v99
	v_and_b32_e32 v51, 0xffff0000, v99
	v_mul_f32_e32 v49, v49, v49
	v_mul_f32_e32 v51, v51, v51
	v_fmac_f32_e32 v49, v48, v48
	v_fmac_f32_e32 v51, v50, v50
	v_add_f32_e32 v49, v49, v51
	v_add_f32_e32 v17, v17, v49
	ds_bpermute_b32 v18, v120, v17
	s_waitcnt lgkmcnt(0)
	v_add_f32_e32 v17, v17, v18
	ds_bpermute_b32 v18, v121, v17
	s_waitcnt lgkmcnt(0)
	v_add_f32_e32 v17, v17, v18
	ds_bpermute_b32 v18, v122, v17
	s_waitcnt lgkmcnt(0)
	v_add_f32_e32 v17, v17, v18
	ds_bpermute_b32 v18, v123, v17
	s_waitcnt lgkmcnt(0)
	v_add_f32_e32 v17, v17, v18
	ds_bpermute_b32 v18, v124, v17
	s_waitcnt lgkmcnt(0)
	v_add_f32_e32 v17, v17, v18
	ds_bpermute_b32 v18, v125, v17
	s_waitcnt lgkmcnt(0)
	v_add_f32_e32 v17, v17, v18
	v_cmp_eq_u32_e32 vcc, 0, v1
	s_nop 1
	v_cndmask_b32_e32 v19, 0, v17, vcc
	s_mov_b64 s[8:9], exec
	s_mov_b32 exec_lo, -1
	s_mov_b32 exec_hi, 0
	global_store_dword v16, v19, s[14:15]
	s_mov_b64 exec, s[8:9]
	s_lshl_b32 s6, s58, 12
	s_add_u32 s12, s48, s6
	s_addc_u32 s13, s49, 0
	s_add_u32 s12, s12, 0x26100800
	s_addc_u32 s13, s13, 0
	s_lshl_b32 s6, s58, 7
	s_add_u32 s14, s48, s6
	s_addc_u32 s15, s49, 0
	s_add_u32 s14, s14, 0x25e00000
	s_addc_u32 s15, s15, 0
	s_add_u32 s58, s58, s44
	s_lshl_b32 s6, s58, 13
	s_lshr_b32 s7, s58, 19
	s_add_u32 s10, s64, s6
	s_addc_u32 s11, s65, s7
	s_add_u32 s10, s10, 0x1000
	s_addc_u32 s11, s11, 0
	global_load_dwordx4 v[20:23], v14, s[10:11] offset:-4096 nt
	global_load_dwordx4 v[24:27], v14, s[10:11] offset:-3072 nt
	global_load_dwordx4 v[28:31], v14, s[10:11] offset:-2048 nt
	global_load_dwordx4 v[32:35], v14, s[10:11] offset:-1024 nt
	global_load_dwordx4 v[36:39], v14, s[10:11] offset:0 nt
	global_load_dwordx4 v[40:43], v14, s[10:11] offset:1024 nt
	global_load_dwordx4 v[44:47], v14, s[10:11] offset:2048 nt
	global_load_dwordx4 v[48:51], v14, s[10:11] offset:3072 nt
	s_waitcnt vmcnt(17)
; __device__ __forceinline__ unsigned pk2(float lo, float hi) { return pg8::cvt_pk_bf16(lo, hi); }
; __device__ __forceinline__ void xcvt_pass(const Ctx& C, const float* X, bf16* XB) {
;     ...
;     for (int m = gw; m < M; m += NGW) {
;         const f32x4* xr = (const f32x4*)(X + (size_t)m * D) + C.lane; v2u* o = (v2u*)(XB + (size_t)m * D) + C.lane; float s = 0.f;
; #pragma unroll
;         for (int j = 0; j < 8; ++j) { const f32x4 v = __builtin_nontemporal_load(xr + 64 * j); const v2u w = (v2u){pk2(v[0], v[1]), pk2(v[2], v[3])}; o[64 * j] = w;
;             const float x0 = __uint_as_float(w.x << 16), x1 = __uint_as_float(w.x & 0xffff0000u), x2 = __uint_as_float(w.y << 16), x3 = __uint_as_float(w.y & 0xffff0000u);
;             s += (x0 * x0 + x1 * x1) + (x2 * x2 + x3 * x3); }
;         s = wave_sum(s);
;         if (C.lane < 32) SS[(size_t)m * 32 + C.lane] = C.lane == 0 ? s : 0.f;
;     }
	v_cvt_pk_bf16_f32 v100, v52, v53
	v_cvt_pk_bf16_f32 v101, v54, v55
	global_store_dwordx2 v15, v[100:101], s[12:13] offset:-2048 sc0 sc1
	v_lshlrev_b32_e32 v52, 16, v100
	v_and_b32_e32 v53, 0xffff0000, v100
	v_lshlrev_b32_e32 v54, 16, v101
	v_and_b32_e32 v55, 0xffff0000, v101
	v_mul_f32_e32 v53, v53, v53
	v_mul_f32_e32 v55, v55, v55
	v_fmac_f32_e32 v53, v52, v52
	v_fmac_f32_e32 v55, v54, v54
	v_add_f32_e32 v17, v53, v55
	v_cvt_pk_bf16_f32 v102, v56, v57
	v_cvt_pk_bf16_f32 v103, v58, v59
	global_store_dwordx2 v15, v[102:103], s[12:13] offset:-1536 sc0 sc1
	v_lshlrev_b32_e32 v56, 16, v102
	v_and_b32_e32 v57, 0xffff0000, v102
	v_lshlrev_b32_e32 v58, 16, v103
	v_and_b32_e32 v59, 0xffff0000, v103
	v_mul_f32_e32 v57, v57, v57
	v_mul_f32_e32 v59, v59, v59
	v_fmac_f32_e32 v57, v56, v56
	v_fmac_f32_e32 v59, v58, v58
	v_add_f32_e32 v57, v57, v59
	v_add_f32_e32 v17, v17, v57
	v_cvt_pk_bf16_f32 v104, v60, v61
	v_cvt_pk_bf16_f32 v105, v62, v63
	global_store_dwordx2 v15, v[104:105], s[12:13] offset:-1024 sc0 sc1
	v_lshlrev_b32_e32 v60, 16, v104
	v_and_b32_e32 v61, 0xffff0000, v104
	v_lshlrev_b32_e32 v62, 16, v105
	v_and_b32_e32 v63, 0xffff0000, v105
	v_mul_f32_e32 v61, v61, v61
	v_mul_f32_e32 v63, v63, v63
	v_fmac_f32_e32 v61, v60, v60
	v_fmac_f32_e32 v63, v62, v62
	v_add_f32_e32 v61, v61, v63
	v_add_f32_e32 v17, v17, v61
	v_cvt_pk_bf16_f32 v106, v64, v65
	v_cvt_pk_bf16_f32 v107, v66, v67
	global_store_dwordx2 v15, v[106:107], s[12:13] offset:-512 sc0 sc1
	v_lshlrev_b32_e32 v64, 16, v106
	v_and_b32_e32 v65, 0xffff0000, v106
	v_lshlrev_b32_e32 v66, 16, v107
	v_and_b32_e32 v67, 0xffff0000, v107
	v_mul_f32_e32 v65, v65, v65
	v_mul_f32_e32 v67, v67, v67
	v_fmac_f32_e32 v65, v64, v64
	v_fmac_f32_e32 v67, v66, v66
	v_add_f32_e32 v65, v65, v67
	v_add_f32_e32 v17, v17, v65
	v_cvt_pk_bf16_f32 v108, v68, v69
	v_cvt_pk_bf16_f32 v109, v70, v71
	global_store_dwordx2 v15, v[108:109], s[12:13] offset:0 sc0 sc1
	v_lshlrev_b32_e32 v68, 16, v108
	v_and_b32_e32 v69, 0xffff0000, v108
	v_lshlrev_b32_e32 v70, 16, v109
	v_and_b32_e32 v71, 0xffff0000, v109
	v_mul_f32_e32 v69, v69, v69
	v_mul_f32_e32 v71, v71, v71
	v_fmac_f32_e32 v69, v68, v68
	v_fmac_f32_e32 v71, v70, v70
	v_add_f32_e32 v69, v69, v71
	v_add_f32_e32 v17, v17, v69
	v_cvt_pk_bf16_f32 v110, v72, v73
	v_cvt_pk_bf16_f32 v111, v74, v75
	global_store_dwordx2 v15, v[110:111], s[12:13] offset:512 sc0 sc1
	v_lshlrev_b32_e32 v72, 16, v110
	v_and_b32_e32 v73, 0xffff0000, v110
	v_lshlrev_b32_e32 v74, 16, v111
	v_and_b32_e32 v75, 0xffff0000, v111
	v_mul_f32_e32 v73, v73, v73
	v_mul_f32_e32 v75, v75, v75
	v_fmac_f32_e32 v73, v72, v72
	v_fmac_f32_e32 v75, v74, v74
	v_add_f32_e32 v73, v73, v75
	v_add_f32_e32 v17, v17, v73
	v_cvt_pk_bf16_f32 v112, v76, v77
	v_cvt_pk_bf16_f32 v113, v78, v79
	global_store_dwordx2 v15, v[112:113], s[12:13] offset:1024 sc0 sc1
	v_lshlrev_b32_e32 v76, 16, v112
	v_and_b32_e32 v77, 0xffff0000, v112
	v_lshlrev_b32_e32 v78, 16, v113
	v_and_b32_e32 v79, 0xffff0000, v113
	v_mul_f32_e32 v77, v77, v77
	v_mul_f32_e32 v79, v79, v79
	v_fmac_f32_e32 v77, v76, v76
	v_fmac_f32_e32 v79, v78, v78
	v_add_f32_e32 v77, v77, v79
	v_add_f32_e32 v17, v17, v77
	v_cvt_pk_bf16_f32 v114, v80, v81
	v_cvt_pk_bf16_f32 v115, v82, v83
	global_store_dwordx2 v15, v[114:115], s[12:13] offset:1536 sc0 sc1
	v_lshlrev_b32_e32 v80, 16, v114
	v_and_b32_e32 v81, 0xffff0000, v114
	v_lshlrev_b32_e32 v82, 16, v115
	v_and_b32_e32 v83, 0xffff0000, v115
	v_mul_f32_e32 v81, v81, v81
	v_mul_f32_e32 v83, v83, v83
	v_fmac_f32_e32 v81, v80, v80
	v_fmac_f32_e32 v83, v82, v82
	v_add_f32_e32 v81, v81, v83
	v_add_f32_e32 v17, v17, v81
	ds_bpermute_b32 v18, v120, v17
	s_waitcnt lgkmcnt(0)
	v_add_f32_e32 v17, v17, v18
	ds_bpermute_b32 v18, v121, v17
	s_waitcnt lgkmcnt(0)
	v_add_f32_e32 v17, v17, v18
	ds_bpermute_b32 v18, v122, v17
	s_waitcnt lgkmcnt(0)
	v_add_f32_e32 v17, v17, v18
	ds_bpermute_b32 v18, v123, v17
	s_waitcnt lgkmcnt(0)
	v_add_f32_e32 v17, v17, v18
	ds_bpermute_b32 v18, v124, v17
	s_waitcnt lgkmcnt(0)
	v_add_f32_e32 v17, v17, v18
	ds_bpermute_b32 v18, v125, v17
	s_waitcnt lgkmcnt(0)
	v_add_f32_e32 v17, v17, v18
	v_cmp_eq_u32_e32 vcc, 0, v1
	s_nop 1
	v_cndmask_b32_e32 v19, 0, v17, vcc
	s_mov_b64 s[8:9], exec
	s_mov_b32 exec_lo, -1
	s_mov_b32 exec_hi, 0
	global_store_dword v16, v19, s[14:15]
	s_mov_b64 exec, s[8:9]
	s_lshl_b32 s6, s58, 12
	s_add_u32 s12, s48, s6
	s_addc_u32 s13, s49, 0
	s_add_u32 s12, s12, 0x26100800
	s_addc_u32 s13, s13, 0
	s_lshl_b32 s6, s58, 7
	s_add_u32 s14, s48, s6
	s_addc_u32 s15, s49, 0
	s_add_u32 s14, s14, 0x25e00000
	s_addc_u32 s15, s15, 0
	s_add_u32 s58, s58, s44
	s_lshl_b32 s6, s58, 13
	s_lshr_b32 s7, s58, 19
	s_add_u32 s10, s64, s6
	s_addc_u32 s11, s65, s7
	s_add_u32 s10, s10, 0x1000
	s_addc_u32 s11, s11, 0
	global_load_dwordx4 v[52:55], v14, s[10:11] offset:-4096 nt
	global_load_dwordx4 v[56:59], v14, s[10:11] offset:-3072 nt
	global_load_dwordx4 v[60:63], v14, s[10:11] offset:-2048 nt
	global_load_dwordx4 v[64:67], v14, s[10:11] offset:-1024 nt
	global_load_dwordx4 v[68:71], v14, s[10:11] offset:0 nt
	global_load_dwordx4 v[72:75], v14, s[10:11] offset:1024 nt
	global_load_dwordx4 v[76:79], v14, s[10:11] offset:2048 nt
	global_load_dwordx4 v[80:83], v14, s[10:11] offset:3072 nt
	s_waitcnt vmcnt(17)
; __device__ __forceinline__ unsigned pk2(float lo, float hi) { return pg8::cvt_pk_bf16(lo, hi); }
; __device__ __forceinline__ void xcvt_pass(const Ctx& C, const float* X, bf16* XB) {
;     ...
;     for (int m = gw; m < M; m += NGW) {
;         const f32x4* xr = (const f32x4*)(X + (size_t)m * D) + C.lane; v2u* o = (v2u*)(XB + (size_t)m * D) + C.lane; float s = 0.f;
; #pragma unroll
;         for (int j = 0; j < 8; ++j) { const f32x4 v = __builtin_nontemporal_load(xr + 64 * j); const v2u w = (v2u){pk2(v[0], v[1]), pk2(v[2], v[3])}; o[64 * j] = w;
;             const float x0 = __uint_as_float(w.x << 16), x1 = __uint_as_float(w.x & 0xffff0000u), x2 = __uint_as_float(w.y << 16), x3 = __uint_as_float(w.y & 0xffff0000u);
;             s += (x0 * x0 + x1 * x1) + (x2 * x2 + x3 * x3); }
;         s = wave_sum(s);
;         if (C.lane < 32) SS[(size_t)m * 32 + C.lane] = C.lane == 0 ? s : 0.f;
;     }
	v_cvt_pk_bf16_f32 v84, v20, v21
	v_cvt_pk_bf16_f32 v85, v22, v23
	global_store_dwordx2 v15, v[84:85], s[12:13] offset:-2048 sc0 sc1
	v_lshlrev_b32_e32 v20, 16, v84
	v_and_b32_e32 v21, 0xffff0000, v84
	v_lshlrev_b32_e32 v22, 16, v85
	v_and_b32_e32 v23, 0xffff0000, v85
	v_mul_f32_e32 v21, v21, v21
	v_mul_f32_e32 v23, v23, v23
	v_fmac_f32_e32 v21, v20, v20
	v_fmac_f32_e32 v23, v22, v22
	v_add_f32_e32 v17, v21, v23
	v_cvt_pk_bf16_f32 v86, v24, v25
	v_cvt_pk_bf16_f32 v87, v26, v27
	global_store_dwordx2 v15, v[86:87], s[12:13] offset:-1536 sc0 sc1
	v_lshlrev_b32_e32 v24, 16, v86
	v_and_b32_e32 v25, 0xffff0000, v86
	v_lshlrev_b32_e32 v26, 16, v87
	v_and_b32_e32 v27, 0xffff0000, v87
	v_mul_f32_e32 v25, v25, v25
	v_mul_f32_e32 v27, v27, v27
	v_fmac_f32_e32 v25, v24, v24
	v_fmac_f32_e32 v27, v26, v26
	v_add_f32_e32 v25, v25, v27
	v_add_f32_e32 v17, v17, v25
	v_cvt_pk_bf16_f32 v88, v28, v29
	v_cvt_pk_bf16_f32 v89, v30, v31
	global_store_dwordx2 v15, v[88:89], s[12:13] offset:-1024 sc0 sc1
	v_lshlrev_b32_e32 v28, 16, v88
	v_and_b32_e32 v29, 0xffff0000, v88
	v_lshlrev_b32_e32 v30, 16, v89
	v_and_b32_e32 v31, 0xffff0000, v89
	v_mul_f32_e32 v29, v29, v29
	v_mul_f32_e32 v31, v31, v31
	v_fmac_f32_e32 v29, v28, v28
	v_fmac_f32_e32 v31, v30, v30
	v_add_f32_e32 v29, v29, v31
	v_add_f32_e32 v17, v17, v29
	v_cvt_pk_bf16_f32 v90, v32, v33
	v_cvt_pk_bf16_f32 v91, v34, v35
	global_store_dwordx2 v15, v[90:91], s[12:13] offset:-512 sc0 sc1
	v_lshlrev_b32_e32 v32, 16, v90
	v_and_b32_e32 v33, 0xffff0000, v90
	v_lshlrev_b32_e32 v34, 16, v91
	v_and_b32_e32 v35, 0xffff0000, v91
	v_mul_f32_e32 v33, v33, v33
	v_mul_f32_e32 v35, v35, v35
	v_fmac_f32_e32 v33, v32, v32
	v_fmac_f32_e32 v35, v34, v34
	v_add_f32_e32 v33, v33, v35
	v_add_f32_e32 v17, v17, v33
	v_cvt_pk_bf16_f32 v92, v36, v37
	v_cvt_pk_bf16_f32 v93, v38, v39
	global_store_dwordx2 v15, v[92:93], s[12:13] offset:0 sc0 sc1
	v_lshlrev_b32_e32 v36, 16, v92
	v_and_b32_e32 v37, 0xffff0000, v92
	v_lshlrev_b32_e32 v38, 16, v93
	v_and_b32_e32 v39, 0xffff0000, v93
	v_mul_f32_e32 v37, v37, v37
	v_mul_f32_e32 v39, v39, v39
	v_fmac_f32_e32 v37, v36, v36
	v_fmac_f32_e32 v39, v38, v38
	v_add_f32_e32 v37, v37, v39
	v_add_f32_e32 v17, v17, v37
	v_cvt_pk_bf16_f32 v94, v40, v41
	v_cvt_pk_bf16_f32 v95, v42, v43
	global_store_dwordx2 v15, v[94:95], s[12:13] offset:512 sc0 sc1
	v_lshlrev_b32_e32 v40, 16, v94
	v_and_b32_e32 v41, 0xffff0000, v94
	v_lshlrev_b32_e32 v42, 16, v95
	v_and_b32_e32 v43, 0xffff0000, v95
	v_mul_f32_e32 v41, v41, v41
	v_mul_f32_e32 v43, v43, v43
	v_fmac_f32_e32 v41, v40, v40
	v_fmac_f32_e32 v43, v42, v42
	v_add_f32_e32 v41, v41, v43
	v_add_f32_e32 v17, v17, v41
	v_cvt_pk_bf16_f32 v96, v44, v45
	v_cvt_pk_bf16_f32 v97, v46, v47
	global_store_dwordx2 v15, v[96:97], s[12:13] offset:1024 sc0 sc1
	v_lshlrev_b32_e32 v44, 16, v96
	v_and_b32_e32 v45, 0xffff0000, v96
	v_lshlrev_b32_e32 v46, 16, v97
	v_and_b32_e32 v47, 0xffff0000, v97
	v_mul_f32_e32 v45, v45, v45
	v_mul_f32_e32 v47, v47, v47
	v_fmac_f32_e32 v45, v44, v44
	v_fmac_f32_e32 v47, v46, v46
	v_add_f32_e32 v45, v45, v47
	v_add_f32_e32 v17, v17, v45
	v_cvt_pk_bf16_f32 v98, v48, v49
	v_cvt_pk_bf16_f32 v99, v50, v51
	global_store_dwordx2 v15, v[98:99], s[12:13] offset:1536 sc0 sc1
	v_lshlrev_b32_e32 v48, 16, v98
	v_and_b32_e32 v49, 0xffff0000, v98
	v_lshlrev_b32_e32 v50, 16, v99
	v_and_b32_e32 v51, 0xffff0000, v99
	v_mul_f32_e32 v49, v49, v49
	v_mul_f32_e32 v51, v51, v51
	v_fmac_f32_e32 v49, v48, v48
	v_fmac_f32_e32 v51, v50, v50
	v_add_f32_e32 v49, v49, v51
	v_add_f32_e32 v17, v17, v49
	ds_bpermute_b32 v18, v120, v17
	s_waitcnt lgkmcnt(0)
	v_add_f32_e32 v17, v17, v18
	ds_bpermute_b32 v18, v121, v17
	s_waitcnt lgkmcnt(0)
	v_add_f32_e32 v17, v17, v18
	ds_bpermute_b32 v18, v122, v17
	s_waitcnt lgkmcnt(0)
	v_add_f32_e32 v17, v17, v18
	ds_bpermute_b32 v18, v123, v17
	s_waitcnt lgkmcnt(0)
	v_add_f32_e32 v17, v17, v18
	ds_bpermute_b32 v18, v124, v17
	s_waitcnt lgkmcnt(0)
	v_add_f32_e32 v17, v17, v18
	ds_bpermute_b32 v18, v125, v17
	s_waitcnt lgkmcnt(0)
	v_add_f32_e32 v17, v17, v18
	v_cmp_eq_u32_e32 vcc, 0, v1
	s_nop 1
	v_cndmask_b32_e32 v19, 0, v17, vcc
	s_mov_b64 s[8:9], exec
	s_mov_b32 exec_lo, -1
	s_mov_b32 exec_hi, 0
	global_store_dword v16, v19, s[14:15]
	s_mov_b64 exec, s[8:9]
	s_lshl_b32 s6, s58, 12
	s_add_u32 s12, s48, s6
	s_addc_u32 s13, s49, 0
	s_add_u32 s12, s12, 0x26100800
	s_addc_u32 s13, s13, 0
	s_lshl_b32 s6, s58, 7
	s_add_u32 s14, s48, s6
	s_addc_u32 s15, s49, 0
	s_add_u32 s14, s14, 0x25e00000
	s_addc_u32 s15, s15, 0
	s_waitcnt vmcnt(9)
; __device__ __forceinline__ unsigned pk2(float lo, float hi) { return pg8::cvt_pk_bf16(lo, hi); }
; __device__ __forceinline__ void xcvt_pass(const Ctx& C, const float* X, bf16* XB) {
;     ...
;     for (int m = gw; m < M; m += NGW) {
;         const f32x4* xr = (const f32x4*)(X + (size_t)m * D) + C.lane; v2u* o = (v2u*)(XB + (size_t)m * D) + C.lane; float s = 0.f;
; #pragma unroll
;         for (int j = 0; j < 8; ++j) { const f32x4 v = __builtin_nontemporal_load(xr + 64 * j); const v2u w = (v2u){pk2(v[0], v[1]), pk2(v[2], v[3])}; o[64 * j] = w;
;             const float x0 = __uint_as_float(w.x << 16), x1 = __uint_as_float(w.x & 0xffff0000u), x2 = __uint_as_float(w.y << 16), x3 = __uint_as_float(w.y & 0xffff0000u);
;             s += (x0 * x0 + x1 * x1) + (x2 * x2 + x3 * x3); }
;         s = wave_sum(s);
;         if (C.lane < 32) SS[(size_t)m * 32 + C.lane] = C.lane == 0 ? s : 0.f;
;     }
	v_cvt_pk_bf16_f32 v100, v52, v53
	v_cvt_pk_bf16_f32 v101, v54, v55
	global_store_dwordx2 v15, v[100:101], s[12:13] offset:-2048 sc0 sc1
	v_lshlrev_b32_e32 v52, 16, v100
	v_and_b32_e32 v53, 0xffff0000, v100
	v_lshlrev_b32_e32 v54, 16, v101
	v_and_b32_e32 v55, 0xffff0000, v101
	v_mul_f32_e32 v53, v53, v53
	v_mul_f32_e32 v55, v55, v55
	v_fmac_f32_e32 v53, v52, v52
	v_fmac_f32_e32 v55, v54, v54
	v_add_f32_e32 v17, v53, v55
	v_cvt_pk_bf16_f32 v102, v56, v57
	v_cvt_pk_bf16_f32 v103, v58, v59
	global_store_dwordx2 v15, v[102:103], s[12:13] offset:-1536 sc0 sc1
	v_lshlrev_b32_e32 v56, 16, v102
	v_and_b32_e32 v57, 0xffff0000, v102
	v_lshlrev_b32_e32 v58, 16, v103
	v_and_b32_e32 v59, 0xffff0000, v103
	v_mul_f32_e32 v57, v57, v57
	v_mul_f32_e32 v59, v59, v59
	v_fmac_f32_e32 v57, v56, v56
	v_fmac_f32_e32 v59, v58, v58
	v_add_f32_e32 v57, v57, v59
	v_add_f32_e32 v17, v17, v57
	v_cvt_pk_bf16_f32 v104, v60, v61
	v_cvt_pk_bf16_f32 v105, v62, v63
	global_store_dwordx2 v15, v[104:105], s[12:13] offset:-1024 sc0 sc1
	v_lshlrev_b32_e32 v60, 16, v104
	v_and_b32_e32 v61, 0xffff0000, v104
	v_lshlrev_b32_e32 v62, 16, v105
	v_and_b32_e32 v63, 0xffff0000, v105
	v_mul_f32_e32 v61, v61, v61
	v_mul_f32_e32 v63, v63, v63
	v_fmac_f32_e32 v61, v60, v60
	v_fmac_f32_e32 v63, v62, v62
	v_add_f32_e32 v61, v61, v63
	v_add_f32_e32 v17, v17, v61
	v_cvt_pk_bf16_f32 v106, v64, v65
	v_cvt_pk_bf16_f32 v107, v66, v67
	global_store_dwordx2 v15, v[106:107], s[12:13] offset:-512 sc0 sc1
	v_lshlrev_b32_e32 v64, 16, v106
	v_and_b32_e32 v65, 0xffff0000, v106
	v_lshlrev_b32_e32 v66, 16, v107
	v_and_b32_e32 v67, 0xffff0000, v107
	v_mul_f32_e32 v65, v65, v65
	v_mul_f32_e32 v67, v67, v67
	v_fmac_f32_e32 v65, v64, v64
	v_fmac_f32_e32 v67, v66, v66
	v_add_f32_e32 v65, v65, v67
	v_add_f32_e32 v17, v17, v65
	v_cvt_pk_bf16_f32 v108, v68, v69
	v_cvt_pk_bf16_f32 v109, v70, v71
	global_store_dwordx2 v15, v[108:109], s[12:13] offset:0 sc0 sc1
	v_lshlrev_b32_e32 v68, 16, v108
	v_and_b32_e32 v69, 0xffff0000, v108
	v_lshlrev_b32_e32 v70, 16, v109
	v_and_b32_e32 v71, 0xffff0000, v109
	v_mul_f32_e32 v69, v69, v69
	v_mul_f32_e32 v71, v71, v71
	v_fmac_f32_e32 v69, v68, v68
	v_fmac_f32_e32 v71, v70, v70
	v_add_f32_e32 v69, v69, v71
	v_add_f32_e32 v17, v17, v69
	v_cvt_pk_bf16_f32 v110, v72, v73
	v_cvt_pk_bf16_f32 v111, v74, v75
	global_store_dwordx2 v15, v[110:111], s[12:13] offset:512 sc0 sc1
	v_lshlrev_b32_e32 v72, 16, v110
	v_and_b32_e32 v73, 0xffff0000, v110
	v_lshlrev_b32_e32 v74, 16, v111
	v_and_b32_e32 v75, 0xffff0000, v111
	v_mul_f32_e32 v73, v73, v73
	v_mul_f32_e32 v75, v75, v75
	v_fmac_f32_e32 v73, v72, v72
	v_fmac_f32_e32 v75, v74, v74
	v_add_f32_e32 v73, v73, v75
	v_add_f32_e32 v17, v17, v73
	v_cvt_pk_bf16_f32 v112, v76, v77
	v_cvt_pk_bf16_f32 v113, v78, v79
	global_store_dwordx2 v15, v[112:113], s[12:13] offset:1024 sc0 sc1
	v_lshlrev_b32_e32 v76, 16, v112
	v_and_b32_e32 v77, 0xffff0000, v112
	v_lshlrev_b32_e32 v78, 16, v113
	v_and_b32_e32 v79, 0xffff0000, v113
	v_mul_f32_e32 v77, v77, v77
	v_mul_f32_e32 v79, v79, v79
	v_fmac_f32_e32 v77, v76, v76
	v_fmac_f32_e32 v79, v78, v78
	v_add_f32_e32 v77, v77, v79
	v_add_f32_e32 v17, v17, v77
	v_cvt_pk_bf16_f32 v114, v80, v81
	v_cvt_pk_bf16_f32 v115, v82, v83
	global_store_dwordx2 v15, v[114:115], s[12:13] offset:1536 sc0 sc1
	v_lshlrev_b32_e32 v80, 16, v114
	v_and_b32_e32 v81, 0xffff0000, v114
	v_lshlrev_b32_e32 v82, 16, v115
	v_and_b32_e32 v83, 0xffff0000, v115
	v_mul_f32_e32 v81, v81, v81
	v_mul_f32_e32 v83, v83, v83
	v_fmac_f32_e32 v81, v80, v80
	v_fmac_f32_e32 v83, v82, v82
	v_add_f32_e32 v81, v81, v83
	v_add_f32_e32 v17, v17, v81
	ds_bpermute_b32 v18, v120, v17
	s_waitcnt lgkmcnt(0)
	v_add_f32_e32 v17, v17, v18
	ds_bpermute_b32 v18, v121, v17
	s_waitcnt lgkmcnt(0)
	v_add_f32_e32 v17, v17, v18
	ds_bpermute_b32 v18, v122, v17
	s_waitcnt lgkmcnt(0)
	v_add_f32_e32 v17, v17, v18
	ds_bpermute_b32 v18, v123, v17
	s_waitcnt lgkmcnt(0)
	v_add_f32_e32 v17, v17, v18
	ds_bpermute_b32 v18, v124, v17
	s_waitcnt lgkmcnt(0)
	v_add_f32_e32 v17, v17, v18
	ds_bpermute_b32 v18, v125, v17
	s_waitcnt lgkmcnt(0)
	v_add_f32_e32 v17, v17, v18
	v_cmp_eq_u32_e32 vcc, 0, v1
	s_nop 1
	v_cndmask_b32_e32 v19, 0, v17, vcc
	s_mov_b64 s[8:9], exec
	s_mov_b32 exec_lo, -1
	s_mov_b32 exec_hi, 0
	global_store_dword v16, v19, s[14:15]
	s_mov_b64 exec, s[8:9]
	s_ashr_i32 s3, s2, 31
	v_mbcnt_lo_u32_b32 v235, -1, 0
	v_writelane_b32 v254, 0, 20

; #define LAS __attribute__((address_space(3)))
; __device__ __forceinline__ unsigned pk2(float lo, float hi) { return pg8::cvt_pk_bf16(lo, hi); }
;     ...
;     for (int j = 0; j < 4; ++j) { const int n = (lane >> 3) + 8 * j; const LAS float* s = scr + (8 * c) * 33 + n;
;         v4u o; o.x = pk2(s[0 * 33], s[1 * 33]); o.y = pk2(s[2 * 33], s[3 * 33]); o.z = pk2(s[4 * 33], s[5 * 33]); o.w = pk2(s[6 * 33], s[7 * 33]);
;         const int drow = mode == 2 ? inproj_col(n0 + n) : drow0 + n;
;         *(v4u*)(WT + (size_t)drow * K + k0 + 8 * c) = o; }
.Lq0_havegs:
	s_waitcnt lgkmcnt(12)
	v_pk_mul_f32 v[52:53], v[52:53], v[12:13]
	v_pk_mul_f32 v[54:55], v[54:55], v[14:15]
	v_pk_mul_f32 v[56:57], v[56:57], v[16:17]
	v_pk_mul_f32 v[58:59], v[58:59], v[18:19]
	v_cvt_pk_bf16_f32 v84, v52, v53
	v_cvt_pk_bf16_f32 v85, v54, v55
	v_cvt_pk_bf16_f32 v86, v56, v57
	v_cvt_pk_bf16_f32 v87, v58, v59
	global_store_dwordx4 v100, v[84:87], s[50:51] sc0 sc1
	s_waitcnt lgkmcnt(8)
	v_pk_mul_f32 v[60:61], v[60:61], v[12:13]
	v_pk_mul_f32 v[62:63], v[62:63], v[14:15]
	v_pk_mul_f32 v[64:65], v[64:65], v[16:17]
	v_pk_mul_f32 v[66:67], v[66:67], v[18:19]
	v_cvt_pk_bf16_f32 v88, v60, v61
	v_cvt_pk_bf16_f32 v89, v62, v63
	v_cvt_pk_bf16_f32 v90, v64, v65
	v_cvt_pk_bf16_f32 v91, v66, v67
	global_store_dwordx4 v101, v[88:91], s[50:51] sc0 sc1
	s_waitcnt lgkmcnt(4)
	v_pk_mul_f32 v[68:69], v[68:69], v[12:13]
	v_pk_mul_f32 v[70:71], v[70:71], v[14:15]
	v_pk_mul_f32 v[72:73], v[72:73], v[16:17]
	v_pk_mul_f32 v[74:75], v[74:75], v[18:19]
	v_cvt_pk_bf16_f32 v92, v68, v69
	v_cvt_pk_bf16_f32 v93, v70, v71
	v_cvt_pk_bf16_f32 v94, v72, v73
	v_cvt_pk_bf16_f32 v95, v74, v75
	global_store_dwordx4 v102, v[92:95], s[50:51] sc0 sc1
	s_waitcnt lgkmcnt(0)
	v_pk_mul_f32 v[76:77], v[76:77], v[12:13]
	v_pk_mul_f32 v[78:79], v[78:79], v[14:15]
	v_pk_mul_f32 v[80:81], v[80:81], v[16:17]
	v_pk_mul_f32 v[82:83], v[82:83], v[18:19]
	v_cvt_pk_bf16_f32 v96, v76, v77
	v_cvt_pk_bf16_f32 v97, v78, v79
	v_cvt_pk_bf16_f32 v98, v80, v81
	v_cvt_pk_bf16_f32 v99, v82, v83
	global_store_dwordx4 v103, v[96:99], s[50:51] sc0 sc1
	s_mov_b32 s50, s70
	s_mov_b32 s51, s71
	s_mov_b32 s52, s72
	s_mov_b32 s53, s73
	s_mov_b32 s54, s74
	s_mov_b32 s55, s75
	s_mov_b32 s56, s76
	s_mov_b32 s57, s77
	s_mov_b32 s58, s59
	s_cmp_eq_u32 s63, 1
	s_cbranch_scc1 .Lq0_loop
	s_waitcnt vmcnt(0)
	v_readlane_b32 s6, v250, 0
	v_readlane_b32 s7, v250, 1
	v_readlane_b32 s8, v250, 2
	v_readlane_b32 s9, v250, 3
	v_readlane_b32 s10, v250, 4
	v_readlane_b32 s11, v250, 5
	v_readlane_b32 s12, v250, 6
	v_readlane_b32 s13, v250, 7
	v_readlane_b32 s14, v250, 8
	v_readlane_b32 s15, v250, 9
	v_readlane_b32 s16, v250, 10
	v_readlane_b32 s17, v250, 11
	v_readlane_b32 s18, v250, 12
	v_readlane_b32 s19, v250, 13
	v_readlane_b32 s20, v250, 14
	v_readlane_b32 s21, v250, 15
	v_readlane_b32 s22, v250, 16
	v_readlane_b32 s23, v250, 17
	v_readlane_b32 s24, v250, 18
	v_readlane_b32 s25, v250, 19
	v_readlane_b32 s26, v250, 20
	v_readlane_b32 s27, v250, 21
	v_readlane_b32 s28, v250, 22
	v_readlane_b32 s29, v250, 23
	v_readlane_b32 s30, v250, 24
	v_readlane_b32 s31, v250, 25
	v_readlane_b32 s32, v250, 26
	v_readlane_b32 s33, v250, 27
	v_readlane_b32 s34, v250, 28
	v_readlane_b32 s35, v250, 29
	v_readlane_b32 s36, v250, 30
	v_readlane_b32 s37, v250, 31
	v_readlane_b32 s38, v250, 32
	v_readlane_b32 s39, v250, 33
	v_readlane_b32 s40, v250, 34
	v_readlane_b32 s41, v250, 35
	v_readlane_b32 s42, v250, 36
	v_readlane_b32 s43, v250, 37
	v_readlane_b32 s44, v250, 38
	v_readlane_b32 s45, v250, 39
	v_readlane_b32 s46, v250, 40
	v_readlane_b32 s47, v250, 41
	v_readlane_b32 s48, v250, 42
	v_readlane_b32 s49, v250, 43
	v_readlane_b32 s50, v250, 44
	v_readlane_b32 s51, v250, 45
	v_readlane_b32 s52, v250, 46
	v_readlane_b32 s53, v250, 47
	v_readlane_b32 s54, v250, 48
	v_readlane_b32 s55, v250, 49
	v_readlane_b32 s56, v250, 50
	v_readlane_b32 s57, v250, 51
	v_readlane_b32 s58, v250, 52
	v_readlane_b32 s59, v250, 53
	v_readlane_b32 s60, v250, 54
	v_readlane_b32 s61, v250, 55
	v_readlane_b32 s62, v250, 56
	v_readlane_b32 s63, v250, 57
	v_readlane_b32 s64, v250, 58
	v_readlane_b32 s65, v250, 59
	v_readlane_b32 s66, v250, 60
	v_readlane_b32 s67, v250, 61
	v_readlane_b32 s68, v250, 62
	v_readlane_b32 s69, v250, 63
	v_readlane_b32 s70, v251, 0
	v_readlane_b32 s71, v251, 1
	v_readlane_b32 s72, v251, 2
	v_readlane_b32 s73, v251, 3
	v_readlane_b32 s74, v251, 4
	v_readlane_b32 s75, v251, 5
	v_readlane_b32 s76, v251, 6
	v_readlane_b32 s77, v251, 7
	v_readlane_b32 s78, v251, 8
	v_readlane_b32 s79, v251, 9

; __device__ __forceinline__ unsigned xb_ld(unsigned* p)              { return __hip_atomic_load(p, __ATOMIC_RELAXED, __HIP_MEMORY_SCOPE_AGENT); }
; __device__ __forceinline__ unsigned xb_add(unsigned* p, unsigned v) { return __hip_atomic_fetch_add(p, v, __ATOMIC_RELAXED, __HIP_MEMORY_SCOPE_AGENT); }
; #define XB_SPIN(cond, bar) do { unsigned _sp = 0; while (cond) { __builtin_amdgcn_s_sleep(1); \
;     if ((++_sp & 255u) == 0u) { if (xb_ld(&(bar)[XB_TMO])) break; if (_sp > XB_SPIN_CAP) { atomicAdd(&(bar)[XB_TMO], 1u); break; } } } } while (0)
; __device__ __forceinline__ void xcd_barrier(const XcdBarrier& b) {
;     asm volatile("s_waitcnt vmcnt(0)" ::: "memory");
;     __syncthreads();
;     if (threadIdx.x == 0) {
;         unsigned* bar = b.bar;
;         __builtin_amdgcn_s_waitcnt(0);
;         unsigned nloc = b.st[0], nx = b.st[1];
;         if (nloc == 0u) { xcd_barrier_complete(bar, b.x, nloc, nx); b.st[0] = nloc; b.st[1] = nx; }
;         const unsigned old = xb_add(&bar[XB_XSUB(b.x)], 1u);
;         const unsigned gen = old / nloc;
;         if (old + 1u == (gen + 1u) * nloc) {
;             __builtin_amdgcn_fence(__ATOMIC_RELEASE, "agent");
;             asm volatile("s_waitcnt vmcnt(0)" ::: "memory");
;             const unsigned og = xb_add(&bar[XB_TOP], 1u);
;             const unsigned tg = og / nx;
;             if (og + 1u == (tg + 1u) * nx) xb_add(&bar[XB_TOPGEN], 1u);
;             else XB_SPIN(xb_ld(&bar[XB_TOPGEN]) == tg, bar);
;             __builtin_amdgcn_fence(__ATOMIC_ACQUIRE, "agent");
;             xb_add(&bar[XB_XGEN(b.x)], 1u);
;             asm volatile("s_waitcnt vmcnt(0)" ::: "memory");
;         } else {
;             XB_SPIN(xb_ld(&bar[XB_XGEN(b.x)]) == gen, bar);
;             __builtin_amdgcn_fence(__ATOMIC_ACQUIRE, "agent");
;             asm volatile("s_waitcnt vmcnt(0)" ::: "memory");
;         }
;     }
.Llb_go_10:
	s_add_u32 s22, s14, 0x25d06100
	s_addc_u32 s23, s15, 0
	v_mov_b32_e32 v2, 0
	v_mov_b32_e32 v3, 1
	global_atomic_add v2, v3, s[22:23]
	s_and_b32 s16, s2, 7
	s_lshl_b32 s16, s16, 8
	s_add_u32 s20, s14, 0x25d05000
	s_addc_u32 s21, s15, 0
	s_add_u32 s20, s20, s16
	s_addc_u32 s21, s21, 0
	v_mov_b32_e32 v2, 0
	v_mov_b32_e32 v3, 1
	global_atomic_add v4, v2, v3, s[20:21] sc0
	s_waitcnt vmcnt(0)
	v_readfirstlane_b32 s17, v4
	s_lshr_b32 s22, s17, 5
	s_add_u32 s17, s17, 1
	s_and_b32 s17, s17, 31
	s_cmp_eq_u32 s17, 0
	s_cbranch_scc0 .Llb_wait_10
	global_atomic_add v2, v3, s[20:21] offset:2048
	s_branch .Llb_acq_10

; __device__ __forceinline__ unsigned xb_ld(unsigned* p)              { return __hip_atomic_load(p, __ATOMIC_RELAXED, __HIP_MEMORY_SCOPE_AGENT); }
; __device__ __forceinline__ void xcd_barrier_complete(unsigned* bar, unsigned x, unsigned& nloc, unsigned& nx) {
;     const unsigned G = gridDim.x * gridDim.y * gridDim.z;
;     unsigned sum, cnt, mine, sp = 0u;
;     for (;;) {
;         sum = 0u; cnt = 0u; mine = 0u;
; #pragma unroll
;         for (unsigned j = 0; j < 16; ++j) { const unsigned c = xb_ld(&bar[XB_XCNT(j)]); sum += c; cnt += (c > 0u) ? 1u : 0u; mine = (j == x) ? c : mine; }
;         if (sum == G) break;
;         __builtin_amdgcn_s_sleep(1);
;         if ((++sp & 255u) == 0u) { if (xb_ld(&bar[XB_TMO])) break; if (sp > XB_SPIN_CAP) { atomicAdd(&bar[XB_TMO], 1u); break; } }
;     }
.LBB0_1405:
	v_readlane_b32 s31, v254, 20
	s_cmp_lg_u32 s31, 0
	s_cbranch_scc1 .Lg10_done
	v_mov_b32_e32 v146, 0x23f08
	ds_read_b32 v146, v146
	s_waitcnt lgkmcnt(0)
	v_readfirstlane_b32 vcc_lo, v146
	s_cmp_eq_u32 vcc_lo, 1
	s_cbranch_scc0 .Lg10_ok
	v_mov_b64_e32 v[144:145], s[16:17]
	v_add_co_u32_e32 v144, vcc, 0x13906100, v144
	s_nop 1
	v_addc_co_u32_e32 v145, vcc, 0, v145, vcc
	s_mov_b32 s31, 0
.Lg10_spin:
	global_load_dword v146, v[144:145], off sc1
	s_waitcnt vmcnt(0)
	v_readfirstlane_b32 vcc_lo, v146
	s_cmp_ge_u32 vcc_lo, 256
	s_cbranch_scc1 .Lg10_ok
	s_sleep 1
	s_add_u32 s31, s31, 1
	s_cmp_lt_u32 s31, 0x100000
	s_cbranch_scc1 .Lg10_spin
.Lg10_ok:
	v_writelane_b32 v254, 1, 20
